# saddr form for all 16 LDS-DMA loads per iteration in all seven K-loops (P1/P2 loops use s98-s101 for the stepped bases)
# speedup vs baseline: 1.0062x; 1.0025x over previous
;     __host__ __device__ bool next(int i, Unit& u) const { const long L = (long)i * G + c; if (L >= nwg) return false; return unit_of((int)L, u); }
;     __host__ __device__ bool next(int i, Unit& u) const { const int L = i == 0 ? l0 : (i == 1 ? l1 : (i == 2 ? l2 : -1)); if (L < 0 || L >= s.nwg) return false; return s.unit_of(L, u); }
;     __host__ __device__ bool next(int i, Unit& u) const { const bool ok = s.next(i >> 1, u); u.kh = i & 1; return ok; }
; #define PG8_STAGE(bufoff, gbase, voff) do { _Pragma("unroll") for (int _i = 0; _i < 2; ++_i) \
;         __builtin_amdgcn_global_load_lds((const unsigned*)((const char*)(gbase) + (voff)[_i]), (PG8_LAS unsigned*)(lds + (bufoff) + ldsw + _i * 8192), 16, 0, 0); } while (0)
; #define PG8_LDA(dst, b, h) do { _Pragma("unroll") for (int m = 0; m < 4; ++m) _Pragma("unroll") for (int k = 0; k < 2; ++k) dst[m][k] = *(const PG8_LAS bf16x8*)(lds + PG8_SA(b, h) + aoff + m * 2048 + k * 1024); } while (0)
; template <class Epi, class Sched, bool ALIGN_EPI = false, bool SP2 = false>
; __device__ __forceinline__ void gemm_phase(PG8_LAS unsigned char* lds, const Gemm g, const Sched& S, const Epi& E) {
;     ...
;         const bool has_next = S.next(ui + 1, nxt);
;         const char* nA = has_next ? (const char*)g.A + (size_t)nxt.pm * tstep + nxt.kh * khb : cA; const char* nB = has_next ? (const char*)g.Bt + (size_t)nxt.pn * tstep + nxt.kh * khb : cB;
;         for (int t = 0; t < nt; t += 2) {
;             const bool last = (t == nt - 2);
;             const char* a1 = cA + (size_t)(t + 1) * kstep;
;             const char* a2 = last ? nA : cA + (size_t)(t + 2) * kstep; const char* b2 = last ? nB : cB + (size_t)(t + 2) * kstep;
;             const char* a3 = a2 + kstep; const char* b3 = b2 + kstep;
;             if (last && has_next) S.a_ready(nxt);
;             if constexpr (SP2) {
;             PG8_LDB(B0, 0, 0); PG8_LDB(B1, 0, 1); PG8_SCHED; PG8_LDA(At, 0, 0); PG8_STAGE(PG8_SA(1, 1), a1 + hstep, voffA);
;             PG8_WAIT_V(8); PG8_WAIT_L(0); PG8_BAR; PG8_MMA(0, 0, At, B0); PG8_MMA(0, 1, At, B1); PG8_BAR; PG8_SCHED;
;             PG8_LDA(At, 0, 1); PG8_STAGE(PG8_SB(0, 0), b2, voffB); PG8_STAGE(PG8_SB(0, 1), b2 + hstep, voffB); PG8_STAGE(PG8_SA(0, 0), a2, voffA);
;             PG8_WAIT_V(8); PG8_WAIT_L(0); PG8_BAR; PG8_MMA(1, 0, At, B0); PG8_MMA(1, 1, At, B1); PG8_BAR; PG8_SCHED;
.LBB0_95:
	s_waitcnt lgkmcnt(0)
	s_ashr_i32 s55, s54, 31
	s_lshl_b64 s[34:35], s[54:55], 19
	s_add_u32 s76, s50, s34
	s_addc_u32 s77, s51, s35
	s_and_b64 s[34:35], s[2:3], exec
	s_cselect_b32 s8, s77, s81
	s_cselect_b32 s55, s76, s80
	s_ashr_i32 s49, s48, 31
	s_lshl_b64 s[34:35], s[48:49], 19
	s_add_u32 s78, s88, s34
	s_addc_u32 s79, s89, s35
	s_and_b64 s[34:35], s[2:3], exec
	s_cselect_b32 s49, s79, s83
	s_cselect_b32 vcc_lo, s78, s82
	s_add_u32 s80, s80, 0x40080
	s_addc_u32 s81, s81, 0
	s_add_u32 vcc_hi, s82, 0x100
	s_addc_u32 s34, s83, 0
	s_mov_b32 s35, -2
	ds_read_b128 v[128:131], v178
	ds_read_b128 v[132:135], v178 offset:1024
	ds_read_b128 v[136:139], v178 offset:2048
	ds_read_b128 v[140:143], v178 offset:3072
	ds_read_b128 v[166:169], v179
	ds_read_b128 v[170:173], v179 offset:1024
	ds_read_b128 v[190:193], v179 offset:2048
	ds_read_b128 v[194:197], v179 offset:3072
	s_add_u32 s36, s80, 0xfffc0080
	s_addc_u32 s37, s81, -1
	s_cmp_eq_u32 s35, 12
	s_cselect_b32 s87, s8, s37
	s_cselect_b32 s86, s55, s36
	s_cselect_b32 s83, s49, s34
	s_cselect_b32 s82, vcc_lo, vcc_hi
	s_add_i32 m0, s93, 0xc000
	ds_read_b128 v[198:201], v181
	ds_read_b128 v[202:205], v181 offset:1024
	ds_read_b128 v[206:209], v181 offset:2048
	ds_read_b128 v[210:213], v181 offset:3072
	ds_read_b128 v[214:217], v181 offset:4096
	ds_read_b128 v[218:221], v181 offset:5120
	ds_read_b128 v[222:225], v181 offset:6144
	ds_read_b128 v[226:229], v181 offset:7168
	global_load_lds_dwordx4 v158, s[80:81]
	s_add_i32 m0, s93, 0xe000
	s_nop 0
	global_load_lds_dwordx4 v160, s[80:81]
	s_waitcnt vmcnt(8)
	s_waitcnt lgkmcnt(0)
	s_barrier
	s_setprio 1
	v_mfma_f32_16x16x32_bf16 v[124:127], v[128:131], v[198:201], 0
	v_mfma_f32_16x16x32_bf16 v[120:123], v[136:139], v[198:201], 0
	v_mfma_f32_16x16x32_bf16 v[108:111], v[128:131], v[206:209], 0
	v_mfma_f32_16x16x32_bf16 v[104:107], v[136:139], v[206:209], 0
	v_mfma_f32_16x16x32_bf16 v[92:95], v[128:131], v[214:217], 0
	v_mfma_f32_16x16x32_bf16 v[88:91], v[136:139], v[214:217], 0
	v_mfma_f32_16x16x32_bf16 v[76:79], v[128:131], v[222:225], 0
	v_mfma_f32_16x16x32_bf16 v[72:75], v[136:139], v[222:225], 0
	v_mfma_f32_16x16x32_bf16 v[124:127], v[132:135], v[202:205], v[124:127]
	v_mfma_f32_16x16x32_bf16 v[120:123], v[140:143], v[202:205], v[120:123]
	v_mfma_f32_16x16x32_bf16 v[108:111], v[132:135], v[210:213], v[108:111]
	v_mfma_f32_16x16x32_bf16 v[104:107], v[140:143], v[210:213], v[104:107]
	v_mfma_f32_16x16x32_bf16 v[92:95], v[132:135], v[218:221], v[92:95]
	v_mfma_f32_16x16x32_bf16 v[88:91], v[140:143], v[218:221], v[88:91]
	v_mfma_f32_16x16x32_bf16 v[76:79], v[132:135], v[226:229], v[76:79]
	v_mfma_f32_16x16x32_bf16 v[72:75], v[140:143], v[226:229], v[72:75]
	v_mfma_f32_16x16x32_bf16 v[116:119], v[166:169], v[198:201], 0
	v_mfma_f32_16x16x32_bf16 v[112:115], v[190:193], v[198:201], 0
	v_mfma_f32_16x16x32_bf16 v[100:103], v[166:169], v[206:209], 0
	v_mfma_f32_16x16x32_bf16 v[96:99], v[190:193], v[206:209], 0
	v_mfma_f32_16x16x32_bf16 v[84:87], v[166:169], v[214:217], 0
	v_mfma_f32_16x16x32_bf16 v[80:83], v[190:193], v[214:217], 0
	v_mfma_f32_16x16x32_bf16 v[68:71], v[166:169], v[222:225], 0
	v_mfma_f32_16x16x32_bf16 v[64:67], v[190:193], v[222:225], 0
	v_mfma_f32_16x16x32_bf16 v[116:119], v[170:173], v[202:205], v[116:119]
	v_mfma_f32_16x16x32_bf16 v[112:115], v[194:197], v[202:205], v[112:115]
	v_mfma_f32_16x16x32_bf16 v[100:103], v[170:173], v[210:213], v[100:103]
	v_mfma_f32_16x16x32_bf16 v[96:99], v[194:197], v[210:213], v[96:99]
	v_mfma_f32_16x16x32_bf16 v[84:87], v[170:173], v[218:221], v[84:87]
	v_mfma_f32_16x16x32_bf16 v[80:83], v[194:197], v[218:221], v[80:83]
	v_mfma_f32_16x16x32_bf16 v[68:71], v[170:173], v[226:229], v[68:71]
	v_mfma_f32_16x16x32_bf16 v[64:67], v[194:197], v[226:229], v[64:67]
	s_setprio 0
	s_barrier
	s_add_u32 s98, s82, s26
	s_addc_u32 s99, s83, s27
	s_add_u32 s100, s86, s26
	s_addc_u32 s101, s87, s27
	s_add_i32 s36, s23, s90
	s_mov_b32 m0, s36
	ds_read_b128 v[198:201], v181 offset:16384
	ds_read_b128 v[202:205], v181 offset:17408
	ds_read_b128 v[206:209], v181 offset:18432
	ds_read_b128 v[210:213], v181 offset:19456
	ds_read_b128 v[214:217], v181 offset:20480
	ds_read_b128 v[218:221], v181 offset:21504
	ds_read_b128 v[222:225], v181 offset:22528
	ds_read_b128 v[226:229], v181 offset:23552
	global_load_lds_dwordx4 v148, s[82:83]
	s_add_i32 m0, s36, 0x2000
	s_add_u32 s36, s82, 0x40000
	s_addc_u32 s37, s83, 0
	s_add_i32 s20, s41, s90
	global_load_lds_dwordx4 v144, s[82:83]
	s_mov_b32 m0, s20
	s_nop 0
	global_load_lds_dwordx4 v148, s[36:37]
	s_add_i32 m0, s20, 0x2000
	s_nop 0
	global_load_lds_dwordx4 v144, s[36:37]
	s_mov_b32 m0, s93
	s_nop 0
	global_load_lds_dwordx4 v150, s[86:87]
	s_mov_b32 m0, s94
	s_nop 0
	global_load_lds_dwordx4 v146, s[86:87]
	s_waitcnt vmcnt(8)
	s_waitcnt lgkmcnt(0)
	s_barrier
	s_setprio 1
	v_mfma_f32_16x16x32_bf16 v[60:63], v[128:131], v[198:201], 0
	v_mfma_f32_16x16x32_bf16 v[56:59], v[136:139], v[198:201], 0
	v_mfma_f32_16x16x32_bf16 v[44:47], v[128:131], v[206:209], 0
	v_mfma_f32_16x16x32_bf16 v[40:43], v[136:139], v[206:209], 0
	v_mfma_f32_16x16x32_bf16 v[28:31], v[128:131], v[214:217], 0
	v_mfma_f32_16x16x32_bf16 v[24:27], v[136:139], v[214:217], 0
	v_mfma_f32_16x16x32_bf16 v[12:15], v[128:131], v[222:225], 0
	v_mfma_f32_16x16x32_bf16 v[8:11], v[136:139], v[222:225], 0
	v_mfma_f32_16x16x32_bf16 v[60:63], v[132:135], v[202:205], v[60:63]
	v_mfma_f32_16x16x32_bf16 v[56:59], v[140:143], v[202:205], v[56:59]
	v_mfma_f32_16x16x32_bf16 v[44:47], v[132:135], v[210:213], v[44:47]
	v_mfma_f32_16x16x32_bf16 v[40:43], v[140:143], v[210:213], v[40:43]
	v_mfma_f32_16x16x32_bf16 v[28:31], v[132:135], v[218:221], v[28:31]
	v_mfma_f32_16x16x32_bf16 v[24:27], v[140:143], v[218:221], v[24:27]
	v_mfma_f32_16x16x32_bf16 v[12:15], v[132:135], v[226:229], v[12:15]
	v_mfma_f32_16x16x32_bf16 v[8:11], v[140:143], v[226:229], v[8:11]
	v_mfma_f32_16x16x32_bf16 v[52:55], v[166:169], v[198:201], 0
	v_mfma_f32_16x16x32_bf16 v[48:51], v[190:193], v[198:201], 0
	v_mfma_f32_16x16x32_bf16 v[36:39], v[166:169], v[206:209], 0
	v_mfma_f32_16x16x32_bf16 v[32:35], v[190:193], v[206:209], 0
	v_mfma_f32_16x16x32_bf16 v[20:23], v[166:169], v[214:217], 0
	v_mfma_f32_16x16x32_bf16 v[16:19], v[190:193], v[214:217], 0
	v_mfma_f32_16x16x32_bf16 v[4:7], v[166:169], v[222:225], 0
	v_mfma_f32_16x16x32_bf16 v[0:3], v[190:193], v[222:225], 0
	v_mfma_f32_16x16x32_bf16 v[52:55], v[170:173], v[202:205], v[52:55]
	v_mfma_f32_16x16x32_bf16 v[48:51], v[194:197], v[202:205], v[48:51]
	v_mfma_f32_16x16x32_bf16 v[36:39], v[170:173], v[210:213], v[36:39]
	v_mfma_f32_16x16x32_bf16 v[32:35], v[194:197], v[210:213], v[32:35]
	v_mfma_f32_16x16x32_bf16 v[20:23], v[170:173], v[218:221], v[20:23]
	v_mfma_f32_16x16x32_bf16 v[16:19], v[194:197], v[218:221], v[16:19]
	v_mfma_f32_16x16x32_bf16 v[4:7], v[170:173], v[226:229], v[4:7]
	v_mfma_f32_16x16x32_bf16 v[0:3], v[194:197], v[226:229], v[0:3]
	s_setprio 0
	s_barrier
	s_branch .Lmy_peel_96_mid
; #define PG8_STAGE(bufoff, gbase, voff) do { _Pragma("unroll") for (int _i = 0; _i < 2; ++_i) \
;         __builtin_amdgcn_global_load_lds((const unsigned*)((const char*)(gbase) + (voff)[_i]), (PG8_LAS unsigned*)(lds + (bufoff) + ldsw + _i * 8192), 16, 0, 0); } while (0)
; #define PG8_LDA(dst, b, h) do { _Pragma("unroll") for (int m = 0; m < 4; ++m) _Pragma("unroll") for (int k = 0; k < 2; ++k) dst[m][k] = *(const PG8_LAS bf16x8*)(lds + PG8_SA(b, h) + aoff + m * 2048 + k * 1024); } while (0)
; #define PG8_LDB(dst, b, h) do { _Pragma("unroll") for (int n = 0; n < 2; ++n) _Pragma("unroll") for (int k = 0; k < 2; ++k) dst[n][k] = *(const PG8_LAS bf16x8*)(lds + PG8_SB(b, h) + boff + n * 2048 + k * 1024); } while (0)
; #define PG8_MMA(ai, bj, At, Bt) do { __builtin_amdgcn_s_setprio(1); _Pragma("unroll") for (int m = 0; m < 4; ++m) _Pragma("unroll") for (int n = 0; n < 2; ++n) _Pragma("unroll") for (int k = 0; k < 2; ++k) \
;         acc[ai][bj][m][n] = __builtin_amdgcn_mfma_f32_16x16x32_bf16(Bt[n][k], At[m][k], acc[ai][bj][m][n], 0, 0, 0); __builtin_amdgcn_s_setprio(0); } while (0)
; #define PG8_WAIT_V(n) asm volatile("s_waitcnt vmcnt(" #n ")" ::: "memory")
; #define PG8_WAIT_L(n) asm volatile("s_waitcnt lgkmcnt(" #n ")" ::: "memory")
; #define PG8_BAR __builtin_amdgcn_s_barrier()
; #define PG8_SCHED __builtin_amdgcn_sched_barrier(0)
; template <class Epi, class Sched, bool ALIGN_EPI = false, bool SP2 = false>
; __device__ __forceinline__ void gemm_phase(PG8_LAS unsigned char* lds, const Gemm g, const Sched& S, const Epi& E) {
;     ...
;             PG8_LDB(B0, 0, 0); PG8_LDB(B1, 0, 1); PG8_SCHED; PG8_LDA(At, 0, 0); PG8_STAGE(PG8_SA(1, 1), a1 + hstep, voffA);
;             PG8_WAIT_V(8); PG8_WAIT_L(0); PG8_BAR; PG8_MMA(0, 0, At, B0); PG8_MMA(0, 1, At, B1); PG8_BAR; PG8_SCHED;
;             PG8_LDA(At, 0, 1); PG8_STAGE(PG8_SB(0, 0), b2, voffB); PG8_STAGE(PG8_SB(0, 1), b2 + hstep, voffB); PG8_STAGE(PG8_SA(0, 0), a2, voffA);
;             PG8_WAIT_V(8); PG8_WAIT_L(0); PG8_BAR; PG8_MMA(1, 0, At, B0); PG8_MMA(1, 1, At, B1); PG8_BAR; PG8_SCHED;
.LBB0_96:
	ds_read_b128 v[128:131], v178
	ds_read_b128 v[132:135], v178 offset:1024
	ds_read_b128 v[136:139], v178 offset:2048
	ds_read_b128 v[140:143], v178 offset:3072
	ds_read_b128 v[166:169], v179
	ds_read_b128 v[170:173], v179 offset:1024
	ds_read_b128 v[190:193], v179 offset:2048
	ds_read_b128 v[194:197], v179 offset:3072
	s_add_u32 s36, s80, 0xfffc0080
	s_addc_u32 s37, s81, -1
	s_cmp_eq_u32 s35, 12
	s_cselect_b32 s87, s8, s37
	s_cselect_b32 s86, s55, s36
	s_cselect_b32 s83, s49, s34
	s_cselect_b32 s82, vcc_lo, vcc_hi
	s_add_i32 m0, s93, 0xc000
	ds_read_b128 v[198:201], v181
	ds_read_b128 v[202:205], v181 offset:1024
	ds_read_b128 v[206:209], v181 offset:2048
	ds_read_b128 v[210:213], v181 offset:3072
	ds_read_b128 v[214:217], v181 offset:4096
	ds_read_b128 v[218:221], v181 offset:5120
	ds_read_b128 v[222:225], v181 offset:6144
	ds_read_b128 v[226:229], v181 offset:7168
	global_load_lds_dwordx4 v158, s[80:81]
	s_add_i32 m0, s93, 0xe000
	s_nop 0
	global_load_lds_dwordx4 v160, s[80:81]
	s_waitcnt vmcnt(8)
	s_waitcnt lgkmcnt(0)
	s_barrier
	s_setprio 1
	v_mfma_f32_16x16x32_bf16 v[124:127], v[128:131], v[198:201], v[124:127]
	v_mfma_f32_16x16x32_bf16 v[120:123], v[136:139], v[198:201], v[120:123]
	v_mfma_f32_16x16x32_bf16 v[108:111], v[128:131], v[206:209], v[108:111]
	v_mfma_f32_16x16x32_bf16 v[104:107], v[136:139], v[206:209], v[104:107]
	v_mfma_f32_16x16x32_bf16 v[92:95], v[128:131], v[214:217], v[92:95]
	v_mfma_f32_16x16x32_bf16 v[88:91], v[136:139], v[214:217], v[88:91]
	v_mfma_f32_16x16x32_bf16 v[76:79], v[128:131], v[222:225], v[76:79]
	v_mfma_f32_16x16x32_bf16 v[72:75], v[136:139], v[222:225], v[72:75]
	v_mfma_f32_16x16x32_bf16 v[124:127], v[132:135], v[202:205], v[124:127]
	v_mfma_f32_16x16x32_bf16 v[120:123], v[140:143], v[202:205], v[120:123]
	v_mfma_f32_16x16x32_bf16 v[108:111], v[132:135], v[210:213], v[108:111]
	v_mfma_f32_16x16x32_bf16 v[104:107], v[140:143], v[210:213], v[104:107]
	v_mfma_f32_16x16x32_bf16 v[92:95], v[132:135], v[218:221], v[92:95]
	v_mfma_f32_16x16x32_bf16 v[88:91], v[140:143], v[218:221], v[88:91]
	v_mfma_f32_16x16x32_bf16 v[76:79], v[132:135], v[226:229], v[76:79]
	v_mfma_f32_16x16x32_bf16 v[72:75], v[140:143], v[226:229], v[72:75]
	v_mfma_f32_16x16x32_bf16 v[116:119], v[166:169], v[198:201], v[116:119]
	v_mfma_f32_16x16x32_bf16 v[112:115], v[190:193], v[198:201], v[112:115]
	v_mfma_f32_16x16x32_bf16 v[100:103], v[166:169], v[206:209], v[100:103]
	v_mfma_f32_16x16x32_bf16 v[96:99], v[190:193], v[206:209], v[96:99]
	v_mfma_f32_16x16x32_bf16 v[84:87], v[166:169], v[214:217], v[84:87]
	v_mfma_f32_16x16x32_bf16 v[80:83], v[190:193], v[214:217], v[80:83]
	v_mfma_f32_16x16x32_bf16 v[68:71], v[166:169], v[222:225], v[68:71]
	v_mfma_f32_16x16x32_bf16 v[64:67], v[190:193], v[222:225], v[64:67]
	v_mfma_f32_16x16x32_bf16 v[116:119], v[170:173], v[202:205], v[116:119]
	v_mfma_f32_16x16x32_bf16 v[112:115], v[194:197], v[202:205], v[112:115]
	v_mfma_f32_16x16x32_bf16 v[100:103], v[170:173], v[210:213], v[100:103]
	v_mfma_f32_16x16x32_bf16 v[96:99], v[194:197], v[210:213], v[96:99]
	v_mfma_f32_16x16x32_bf16 v[84:87], v[170:173], v[218:221], v[84:87]
	v_mfma_f32_16x16x32_bf16 v[80:83], v[194:197], v[218:221], v[80:83]
	v_mfma_f32_16x16x32_bf16 v[68:71], v[170:173], v[226:229], v[68:71]
	v_mfma_f32_16x16x32_bf16 v[64:67], v[194:197], v[226:229], v[64:67]
	s_setprio 0
	s_barrier
	s_add_u32 s98, s82, s26
	s_addc_u32 s99, s83, s27
	s_add_u32 s100, s86, s26
	s_addc_u32 s101, s87, s27
	s_add_i32 s36, s23, s90
	s_mov_b32 m0, s36
	ds_read_b128 v[198:201], v181 offset:16384
	ds_read_b128 v[202:205], v181 offset:17408
	ds_read_b128 v[206:209], v181 offset:18432
	ds_read_b128 v[210:213], v181 offset:19456
	ds_read_b128 v[214:217], v181 offset:20480
	ds_read_b128 v[218:221], v181 offset:21504
	ds_read_b128 v[222:225], v181 offset:22528
	ds_read_b128 v[226:229], v181 offset:23552
	global_load_lds_dwordx4 v148, s[82:83]
	s_add_i32 m0, s36, 0x2000
	s_add_u32 s36, s82, 0x40000
	s_addc_u32 s37, s83, 0
	s_add_i32 s20, s41, s90
	global_load_lds_dwordx4 v144, s[82:83]
	s_mov_b32 m0, s20
	s_nop 0
	global_load_lds_dwordx4 v148, s[36:37]
	s_add_i32 m0, s20, 0x2000
	s_nop 0
	global_load_lds_dwordx4 v144, s[36:37]
	s_mov_b32 m0, s93
	s_nop 0
	global_load_lds_dwordx4 v150, s[86:87]
	s_mov_b32 m0, s94
	s_nop 0
	global_load_lds_dwordx4 v146, s[86:87]
	s_waitcnt vmcnt(8)
	s_waitcnt lgkmcnt(0)
	s_barrier
	s_setprio 1
	v_mfma_f32_16x16x32_bf16 v[60:63], v[128:131], v[198:201], v[60:63]
	v_mfma_f32_16x16x32_bf16 v[56:59], v[136:139], v[198:201], v[56:59]
	v_mfma_f32_16x16x32_bf16 v[44:47], v[128:131], v[206:209], v[44:47]
	v_mfma_f32_16x16x32_bf16 v[40:43], v[136:139], v[206:209], v[40:43]
	v_mfma_f32_16x16x32_bf16 v[28:31], v[128:131], v[214:217], v[28:31]
	v_mfma_f32_16x16x32_bf16 v[24:27], v[136:139], v[214:217], v[24:27]
	v_mfma_f32_16x16x32_bf16 v[12:15], v[128:131], v[222:225], v[12:15]
	v_mfma_f32_16x16x32_bf16 v[8:11], v[136:139], v[222:225], v[8:11]
	v_mfma_f32_16x16x32_bf16 v[60:63], v[132:135], v[202:205], v[60:63]
	v_mfma_f32_16x16x32_bf16 v[56:59], v[140:143], v[202:205], v[56:59]
	v_mfma_f32_16x16x32_bf16 v[44:47], v[132:135], v[210:213], v[44:47]
	v_mfma_f32_16x16x32_bf16 v[40:43], v[140:143], v[210:213], v[40:43]
	v_mfma_f32_16x16x32_bf16 v[28:31], v[132:135], v[218:221], v[28:31]
	v_mfma_f32_16x16x32_bf16 v[24:27], v[140:143], v[218:221], v[24:27]
	v_mfma_f32_16x16x32_bf16 v[12:15], v[132:135], v[226:229], v[12:15]
	v_mfma_f32_16x16x32_bf16 v[8:11], v[140:143], v[226:229], v[8:11]
	v_mfma_f32_16x16x32_bf16 v[52:55], v[166:169], v[198:201], v[52:55]
	v_mfma_f32_16x16x32_bf16 v[48:51], v[190:193], v[198:201], v[48:51]
	v_mfma_f32_16x16x32_bf16 v[36:39], v[166:169], v[206:209], v[36:39]
	v_mfma_f32_16x16x32_bf16 v[32:35], v[190:193], v[206:209], v[32:35]
	v_mfma_f32_16x16x32_bf16 v[20:23], v[166:169], v[214:217], v[20:23]
	v_mfma_f32_16x16x32_bf16 v[16:19], v[190:193], v[214:217], v[16:19]
	v_mfma_f32_16x16x32_bf16 v[4:7], v[166:169], v[222:225], v[4:7]
	v_mfma_f32_16x16x32_bf16 v[0:3], v[190:193], v[222:225], v[0:3]
	v_mfma_f32_16x16x32_bf16 v[52:55], v[170:173], v[202:205], v[52:55]
	v_mfma_f32_16x16x32_bf16 v[48:51], v[194:197], v[202:205], v[48:51]
	v_mfma_f32_16x16x32_bf16 v[36:39], v[170:173], v[210:213], v[36:39]
	v_mfma_f32_16x16x32_bf16 v[32:35], v[194:197], v[210:213], v[32:35]
	v_mfma_f32_16x16x32_bf16 v[20:23], v[170:173], v[218:221], v[20:23]
	v_mfma_f32_16x16x32_bf16 v[16:19], v[194:197], v[218:221], v[16:19]
	v_mfma_f32_16x16x32_bf16 v[4:7], v[170:173], v[226:229], v[4:7]
	v_mfma_f32_16x16x32_bf16 v[0:3], v[194:197], v[226:229], v[0:3]
	s_setprio 0
	s_barrier
; #define PG8_STAGE(bufoff, gbase, voff) do { _Pragma("unroll") for (int _i = 0; _i < 2; ++_i) \
;         __builtin_amdgcn_global_load_lds((const unsigned*)((const char*)(gbase) + (voff)[_i]), (PG8_LAS unsigned*)(lds + (bufoff) + ldsw + _i * 8192), 16, 0, 0); } while (0)
; #define PG8_LDA(dst, b, h) do { _Pragma("unroll") for (int m = 0; m < 4; ++m) _Pragma("unroll") for (int k = 0; k < 2; ++k) dst[m][k] = *(const PG8_LAS bf16x8*)(lds + PG8_SA(b, h) + aoff + m * 2048 + k * 1024); } while (0)
; #define PG8_LDB(dst, b, h) do { _Pragma("unroll") for (int n = 0; n < 2; ++n) _Pragma("unroll") for (int k = 0; k < 2; ++k) dst[n][k] = *(const PG8_LAS bf16x8*)(lds + PG8_SB(b, h) + boff + n * 2048 + k * 1024); } while (0)
; #define PG8_MMA(ai, bj, At, Bt) do { __builtin_amdgcn_s_setprio(1); _Pragma("unroll") for (int m = 0; m < 4; ++m) _Pragma("unroll") for (int n = 0; n < 2; ++n) _Pragma("unroll") for (int k = 0; k < 2; ++k) \
;         acc[ai][bj][m][n] = __builtin_amdgcn_mfma_f32_16x16x32_bf16(Bt[n][k], At[m][k], acc[ai][bj][m][n], 0, 0, 0); __builtin_amdgcn_s_setprio(0); } while (0)
; #define PG8_WAIT_V(n) asm volatile("s_waitcnt vmcnt(" #n ")" ::: "memory")
; #define PG8_WAIT_L(n) asm volatile("s_waitcnt lgkmcnt(" #n ")" ::: "memory")
; #define PG8_BAR __builtin_amdgcn_s_barrier()
; #define PG8_SCHED __builtin_amdgcn_sched_barrier(0)
; template <class Epi, class Sched, bool ALIGN_EPI = false, bool SP2 = false>
; __device__ __forceinline__ void gemm_phase(PG8_LAS unsigned char* lds, const Gemm g, const Sched& S, const Epi& E) {
;     ...
;         for (int t = 0; t < nt; t += 2) {
;             const bool last = (t == nt - 2);
;             const char* a1 = cA + (size_t)(t + 1) * kstep;
;             const char* a2 = last ? nA : cA + (size_t)(t + 2) * kstep; const char* b2 = last ? nB : cB + (size_t)(t + 2) * kstep;
;     ...
;             PG8_LDB(B0, 1, 0); PG8_LDB(B1, 1, 1); PG8_SCHED; PG8_LDA(At, 1, 0); PG8_STAGE(PG8_SA(0, 1), a2 + hstep, voffA);
;             PG8_WAIT_V(8); PG8_WAIT_L(0); PG8_BAR; PG8_MMA(0, 0, At, B0); PG8_MMA(0, 1, At, B1); PG8_BAR; PG8_SCHED;
;             PG8_LDA(At, 1, 1); PG8_STAGE(PG8_SB(1, 0), b3, voffB); PG8_STAGE(PG8_SB(1, 1), b3 + hstep, voffB); PG8_STAGE(PG8_SA(1, 0), a3, voffA);
;             PG8_WAIT_V(8); PG8_WAIT_L(0); PG8_BAR; PG8_MMA(1, 0, At, B0); PG8_MMA(1, 1, At, B1); PG8_BAR; PG8_SCHED;
.Lmy_peel_96_mid:
	s_add_i32 s20, 0, 0x18000
	s_add_i32 s21, 0, 0x1c000
	v_add_u32_e32 v140, s20, v176
	v_add_u32_e32 v152, s21, v176
	ds_read_b128 v[128:131], v140
	ds_read_b128 v[132:135], v140 offset:1024
	ds_read_b128 v[136:139], v140 offset:2048
	ds_read_b128 v[140:143], v140 offset:3072
	ds_read_b128 v[166:169], v152
	ds_read_b128 v[170:173], v152 offset:1024
	ds_read_b128 v[190:193], v152 offset:2048
	ds_read_b128 v[194:197], v152 offset:3072
	s_add_u32 s36, s86, 0x40000
	s_addc_u32 s37, s87, 0
	s_mov_b32 m0, s95
	ds_read_b128 v[198:201], v181 offset:32768
	ds_read_b128 v[202:205], v181 offset:33792
	ds_read_b128 v[206:209], v181 offset:34816
	ds_read_b128 v[210:213], v181 offset:35840
	ds_read_b128 v[214:217], v181 offset:36864
	ds_read_b128 v[218:221], v181 offset:37888
	ds_read_b128 v[222:225], v181 offset:38912
	ds_read_b128 v[226:229], v181 offset:39936
	global_load_lds_dwordx4 v150, s[36:37]
	s_mov_b32 m0, s97
	s_nop 0
	global_load_lds_dwordx4 v146, s[36:37]
	s_waitcnt vmcnt(8)
	s_waitcnt lgkmcnt(0)
	s_barrier
	s_setprio 1
	v_mfma_f32_16x16x32_bf16 v[124:127], v[128:131], v[198:201], v[124:127]
	v_mfma_f32_16x16x32_bf16 v[120:123], v[136:139], v[198:201], v[120:123]
	v_mfma_f32_16x16x32_bf16 v[108:111], v[128:131], v[206:209], v[108:111]
	v_mfma_f32_16x16x32_bf16 v[104:107], v[136:139], v[206:209], v[104:107]
	v_mfma_f32_16x16x32_bf16 v[92:95], v[128:131], v[214:217], v[92:95]
	v_mfma_f32_16x16x32_bf16 v[88:91], v[136:139], v[214:217], v[88:91]
	v_mfma_f32_16x16x32_bf16 v[76:79], v[128:131], v[222:225], v[76:79]
	v_mfma_f32_16x16x32_bf16 v[72:75], v[136:139], v[222:225], v[72:75]
	v_mfma_f32_16x16x32_bf16 v[124:127], v[132:135], v[202:205], v[124:127]
	v_mfma_f32_16x16x32_bf16 v[120:123], v[140:143], v[202:205], v[120:123]
	v_mfma_f32_16x16x32_bf16 v[108:111], v[132:135], v[210:213], v[108:111]
	v_mfma_f32_16x16x32_bf16 v[104:107], v[140:143], v[210:213], v[104:107]
	v_mfma_f32_16x16x32_bf16 v[92:95], v[132:135], v[218:221], v[92:95]
	v_mfma_f32_16x16x32_bf16 v[88:91], v[140:143], v[218:221], v[88:91]
	v_mfma_f32_16x16x32_bf16 v[76:79], v[132:135], v[226:229], v[76:79]
	v_mfma_f32_16x16x32_bf16 v[72:75], v[140:143], v[226:229], v[72:75]
	v_mfma_f32_16x16x32_bf16 v[116:119], v[166:169], v[198:201], v[116:119]
	v_mfma_f32_16x16x32_bf16 v[112:115], v[190:193], v[198:201], v[112:115]
	v_mfma_f32_16x16x32_bf16 v[100:103], v[166:169], v[206:209], v[100:103]
	v_mfma_f32_16x16x32_bf16 v[96:99], v[190:193], v[206:209], v[96:99]
	v_mfma_f32_16x16x32_bf16 v[84:87], v[166:169], v[214:217], v[84:87]
	v_mfma_f32_16x16x32_bf16 v[80:83], v[190:193], v[214:217], v[80:83]
	v_mfma_f32_16x16x32_bf16 v[68:71], v[166:169], v[222:225], v[68:71]
	v_mfma_f32_16x16x32_bf16 v[64:67], v[190:193], v[222:225], v[64:67]
	v_mfma_f32_16x16x32_bf16 v[116:119], v[170:173], v[202:205], v[116:119]
	v_mfma_f32_16x16x32_bf16 v[112:115], v[194:197], v[202:205], v[112:115]
	v_mfma_f32_16x16x32_bf16 v[100:103], v[170:173], v[210:213], v[100:103]
	v_mfma_f32_16x16x32_bf16 v[96:99], v[194:197], v[210:213], v[96:99]
	v_mfma_f32_16x16x32_bf16 v[84:87], v[170:173], v[218:221], v[84:87]
	v_mfma_f32_16x16x32_bf16 v[80:83], v[194:197], v[218:221], v[80:83]
	v_mfma_f32_16x16x32_bf16 v[68:71], v[170:173], v[226:229], v[68:71]
	v_mfma_f32_16x16x32_bf16 v[64:67], v[194:197], v[226:229], v[64:67]
	s_setprio 0
	s_barrier
	s_add_i32 s20, s20, s90
	s_mov_b32 m0, s20
	ds_read_b128 v[198:201], v181 offset:49152
	ds_read_b128 v[202:205], v181 offset:50176
	ds_read_b128 v[206:209], v181 offset:51200
	ds_read_b128 v[210:213], v181 offset:52224
	ds_read_b128 v[214:217], v181 offset:53248
	ds_read_b128 v[218:221], v181 offset:54272
	ds_read_b128 v[222:225], v181 offset:55296
	ds_read_b128 v[226:229], v181 offset:56320
	global_load_lds_dwordx4 v148, s[98:99]
	s_add_i32 m0, s20, 0x2000
	s_add_u32 s36, s82, 0x40080
	s_addc_u32 s37, s83, 0
	s_add_i32 s20, s21, s90
	global_load_lds_dwordx4 v144, s[98:99]
	s_mov_b32 m0, s20
	s_nop 0
	global_load_lds_dwordx4 v148, s[36:37]
	s_add_i32 m0, s20, 0x2000
	s_nop 0
	global_load_lds_dwordx4 v144, s[36:37]
	s_mov_b32 m0, s42
	s_nop 0
	global_load_lds_dwordx4 v150, s[100:101]
	s_mov_b32 m0, s43
	s_nop 0
	global_load_lds_dwordx4 v146, s[100:101]
	s_waitcnt vmcnt(8)
	s_waitcnt lgkmcnt(0)
	s_barrier
	s_setprio 1
	v_mfma_f32_16x16x32_bf16 v[60:63], v[128:131], v[198:201], v[60:63]
	v_mfma_f32_16x16x32_bf16 v[56:59], v[136:139], v[198:201], v[56:59]
	v_mfma_f32_16x16x32_bf16 v[44:47], v[128:131], v[206:209], v[44:47]
	v_mfma_f32_16x16x32_bf16 v[40:43], v[136:139], v[206:209], v[40:43]
	v_mfma_f32_16x16x32_bf16 v[28:31], v[128:131], v[214:217], v[28:31]
	v_mfma_f32_16x16x32_bf16 v[24:27], v[136:139], v[214:217], v[24:27]
	v_mfma_f32_16x16x32_bf16 v[12:15], v[128:131], v[222:225], v[12:15]
	v_mfma_f32_16x16x32_bf16 v[8:11], v[136:139], v[222:225], v[8:11]
	v_mfma_f32_16x16x32_bf16 v[60:63], v[132:135], v[202:205], v[60:63]
	v_mfma_f32_16x16x32_bf16 v[56:59], v[140:143], v[202:205], v[56:59]
	v_mfma_f32_16x16x32_bf16 v[44:47], v[132:135], v[210:213], v[44:47]
	v_mfma_f32_16x16x32_bf16 v[40:43], v[140:143], v[210:213], v[40:43]
	v_mfma_f32_16x16x32_bf16 v[28:31], v[132:135], v[218:221], v[28:31]
	v_mfma_f32_16x16x32_bf16 v[24:27], v[140:143], v[218:221], v[24:27]
	v_mfma_f32_16x16x32_bf16 v[12:15], v[132:135], v[226:229], v[12:15]
	v_mfma_f32_16x16x32_bf16 v[8:11], v[140:143], v[226:229], v[8:11]
	v_mfma_f32_16x16x32_bf16 v[52:55], v[166:169], v[198:201], v[52:55]
	v_mfma_f32_16x16x32_bf16 v[48:51], v[190:193], v[198:201], v[48:51]
	v_mfma_f32_16x16x32_bf16 v[36:39], v[166:169], v[206:209], v[36:39]
	v_mfma_f32_16x16x32_bf16 v[32:35], v[190:193], v[206:209], v[32:35]
	v_mfma_f32_16x16x32_bf16 v[20:23], v[166:169], v[214:217], v[20:23]
	v_mfma_f32_16x16x32_bf16 v[16:19], v[190:193], v[214:217], v[16:19]
	v_mfma_f32_16x16x32_bf16 v[4:7], v[166:169], v[222:225], v[4:7]
	v_mfma_f32_16x16x32_bf16 v[0:3], v[190:193], v[222:225], v[0:3]
	v_mfma_f32_16x16x32_bf16 v[52:55], v[170:173], v[202:205], v[52:55]
	v_mfma_f32_16x16x32_bf16 v[48:51], v[194:197], v[202:205], v[48:51]
	v_mfma_f32_16x16x32_bf16 v[36:39], v[170:173], v[210:213], v[36:39]
	v_mfma_f32_16x16x32_bf16 v[32:35], v[194:197], v[210:213], v[32:35]
	v_mfma_f32_16x16x32_bf16 v[20:23], v[170:173], v[218:221], v[20:23]
	v_mfma_f32_16x16x32_bf16 v[16:19], v[194:197], v[218:221], v[16:19]
	v_mfma_f32_16x16x32_bf16 v[4:7], v[170:173], v[226:229], v[4:7]
	v_mfma_f32_16x16x32_bf16 v[0:3], v[194:197], v[226:229], v[0:3]
	s_setprio 0
	s_barrier
	s_add_i32 s35, s35, 2
	s_add_u32 s80, s80, 0x100
	s_addc_u32 s81, s81, 0
	s_add_u32 vcc_hi, vcc_hi, 0x100
	s_addc_u32 s34, s34, 0
	s_cmp_gt_u32 s35, 13
	s_cbranch_scc0 .LBB0_96
	s_and_b64 vcc, exec, s[28:29]
	s_cbranch_vccz .LBB0_99
	s_barrier

;     __host__ __device__ bool next(int i, Unit& u) const { const long L = (long)i * G + c; if (L >= nwg) return false; return unit_of((int)L, u); }
;     __host__ __device__ bool next(int i, Unit& u) const { const int L = i == 0 ? l0 : (i == 1 ? l1 : (i == 2 ? l2 : -1)); if (L < 0 || L >= s.nwg) return false; return s.unit_of(L, u); }
;     __host__ __device__ bool next(int i, Unit& u) const { const bool ok = s.next(i >> 1, u); u.kh = i & 1; return ok; }
; #define PG8_STAGE(bufoff, gbase, voff) do { _Pragma("unroll") for (int _i = 0; _i < 2; ++_i) \
;         __builtin_amdgcn_global_load_lds((const unsigned*)((const char*)(gbase) + (voff)[_i]), (PG8_LAS unsigned*)(lds + (bufoff) + ldsw + _i * 8192), 16, 0, 0); } while (0)
; #define PG8_LDA(dst, b, h) do { _Pragma("unroll") for (int m = 0; m < 4; ++m) _Pragma("unroll") for (int k = 0; k < 2; ++k) dst[m][k] = *(const PG8_LAS bf16x8*)(lds + PG8_SA(b, h) + aoff + m * 2048 + k * 1024); } while (0)
; template <class Epi, class Sched, bool ALIGN_EPI = false, bool SP2 = false>
; __device__ __forceinline__ void gemm_phase(PG8_LAS unsigned char* lds, const Gemm g, const Sched& S, const Epi& E) {
;     ...
;         const bool has_next = S.next(ui + 1, nxt);
;         const char* nA = has_next ? (const char*)g.A + (size_t)nxt.pm * tstep + nxt.kh * khb : cA; const char* nB = has_next ? (const char*)g.Bt + (size_t)nxt.pn * tstep + nxt.kh * khb : cB;
;         for (int t = 0; t < nt; t += 2) {
;             const bool last = (t == nt - 2);
;             const char* a1 = cA + (size_t)(t + 1) * kstep;
;             const char* a2 = last ? nA : cA + (size_t)(t + 2) * kstep; const char* b2 = last ? nB : cB + (size_t)(t + 2) * kstep;
;             const char* a3 = a2 + kstep; const char* b3 = b2 + kstep;
;             if (last && has_next) S.a_ready(nxt);
;             if constexpr (SP2) {
;             PG8_LDB(B0, 0, 0); PG8_LDB(B1, 0, 1); PG8_SCHED; PG8_LDA(At, 0, 0); PG8_STAGE(PG8_SA(1, 1), a1 + hstep, voffA);
;             PG8_WAIT_V(8); PG8_WAIT_L(0); PG8_BAR; PG8_MMA(0, 0, At, B0); PG8_MMA(0, 1, At, B1); PG8_BAR; PG8_SCHED;
;             PG8_LDA(At, 0, 1); PG8_STAGE(PG8_SB(0, 0), b2, voffB); PG8_STAGE(PG8_SB(0, 1), b2 + hstep, voffB); PG8_STAGE(PG8_SA(0, 0), a2, voffA);
;             PG8_WAIT_V(8); PG8_WAIT_L(0); PG8_BAR; PG8_MMA(1, 0, At, B0); PG8_MMA(1, 1, At, B1); PG8_BAR; PG8_SCHED;
.LBB0_149:
	s_ashr_i32 s17, s16, 31
	s_lshl_b64 s[18:19], s[16:17], 19
	s_add_u32 s18, s29, s18
	s_addc_u32 s19, s30, s19
	s_and_b64 s[20:21], s[2:3], exec
	s_cselect_b32 s17, s19, s23
	s_cselect_b32 s45, s18, s22
	s_ashr_i32 s15, s14, 31
	s_lshl_b64 s[20:21], s[14:15], 19
	s_add_u32 s20, s50, s20
	s_addc_u32 s21, s51, s21
	s_and_b64 s[26:27], s[2:3], exec
	s_cselect_b32 s15, s21, s25
	s_cselect_b32 s46, s20, s24
	s_add_u32 s22, s22, 0x40080
	s_addc_u32 s23, s23, 0
	s_add_u32 s47, s24, 0x100
	s_addc_u32 s48, s25, 0
	s_mov_b32 s49, -2
	s_add_u32 s24, s22, 0xfffc0080
	s_addc_u32 s25, s23, -1
	s_waitcnt lgkmcnt(0)
	s_add_i32 s54, 0, 0x10000
	v_add_u32_e32 v147, s54, v152
	ds_read_b128 v[156:159], v147
	ds_read_b128 v[160:163], v147 offset:1024
	ds_read_b128 v[164:167], v147 offset:2048
	ds_read_b128 v[168:171], v147 offset:3072
	ds_read_b128 v[172:175], v154
	ds_read_b128 v[176:179], v154 offset:1024
	ds_read_b128 v[182:185], v154 offset:2048
	ds_read_b128 v[190:193], v154 offset:3072
	s_cmp_eq_u32 s49, 12
	s_cselect_b32 s27, s17, s25
	s_cselect_b32 s26, s45, s24
	s_cselect_b32 s25, s15, s48
	s_cselect_b32 s24, s46, s47
	s_add_i32 m0, s13, 0xc000
	ds_read_b128 v[194:197], v155
	ds_read_b128 v[198:201], v155 offset:1024
	ds_read_b128 v[202:205], v155 offset:2048
	ds_read_b128 v[206:209], v155 offset:3072
	ds_read_b128 v[210:213], v155 offset:4096
	ds_read_b128 v[214:217], v155 offset:5120
	ds_read_b128 v[218:221], v155 offset:6144
	ds_read_b128 v[222:225], v155 offset:7168
	global_load_lds_dwordx4 v138, s[22:23]
	s_add_i32 m0, s13, 0xe000
	s_nop 0
	global_load_lds_dwordx4 v140, s[22:23]
	s_waitcnt vmcnt(8)
	s_waitcnt lgkmcnt(0)
	s_barrier
	s_setprio 1
	v_mfma_f32_16x16x32_bf16 v[124:127], v[156:159], v[194:197], 0
	v_mfma_f32_16x16x32_bf16 v[120:123], v[164:167], v[194:197], 0
	v_mfma_f32_16x16x32_bf16 v[116:119], v[156:159], v[202:205], 0
	v_mfma_f32_16x16x32_bf16 v[112:115], v[164:167], v[202:205], 0
	v_mfma_f32_16x16x32_bf16 v[100:103], v[156:159], v[210:213], 0
	v_mfma_f32_16x16x32_bf16 v[96:99], v[164:167], v[210:213], 0
	v_mfma_f32_16x16x32_bf16 v[84:87], v[156:159], v[218:221], 0
	v_mfma_f32_16x16x32_bf16 v[80:83], v[164:167], v[218:221], 0
	v_mfma_f32_16x16x32_bf16 v[124:127], v[160:163], v[198:201], v[124:127]
	v_mfma_f32_16x16x32_bf16 v[120:123], v[168:171], v[198:201], v[120:123]
	v_mfma_f32_16x16x32_bf16 v[116:119], v[160:163], v[206:209], v[116:119]
	v_mfma_f32_16x16x32_bf16 v[112:115], v[168:171], v[206:209], v[112:115]
	v_mfma_f32_16x16x32_bf16 v[100:103], v[160:163], v[214:217], v[100:103]
	v_mfma_f32_16x16x32_bf16 v[96:99], v[168:171], v[214:217], v[96:99]
	v_mfma_f32_16x16x32_bf16 v[84:87], v[160:163], v[222:225], v[84:87]
	v_mfma_f32_16x16x32_bf16 v[80:83], v[168:171], v[222:225], v[80:83]
	v_mfma_f32_16x16x32_bf16 v[108:111], v[172:175], v[194:197], 0
	v_mfma_f32_16x16x32_bf16 v[104:107], v[182:185], v[194:197], 0
	v_mfma_f32_16x16x32_bf16 v[92:95], v[172:175], v[202:205], 0
	v_mfma_f32_16x16x32_bf16 v[88:91], v[182:185], v[202:205], 0
	v_mfma_f32_16x16x32_bf16 v[76:79], v[172:175], v[210:213], 0
	v_mfma_f32_16x16x32_bf16 v[72:75], v[182:185], v[210:213], 0
	v_mfma_f32_16x16x32_bf16 v[68:71], v[172:175], v[218:221], 0
	v_mfma_f32_16x16x32_bf16 v[64:67], v[182:185], v[218:221], 0
	v_mfma_f32_16x16x32_bf16 v[108:111], v[176:179], v[198:201], v[108:111]
	v_mfma_f32_16x16x32_bf16 v[104:107], v[190:193], v[198:201], v[104:107]
	v_mfma_f32_16x16x32_bf16 v[92:95], v[176:179], v[206:209], v[92:95]
	v_mfma_f32_16x16x32_bf16 v[88:91], v[190:193], v[206:209], v[88:91]
	v_mfma_f32_16x16x32_bf16 v[76:79], v[176:179], v[214:217], v[76:79]
	v_mfma_f32_16x16x32_bf16 v[72:75], v[190:193], v[214:217], v[72:75]
	v_mfma_f32_16x16x32_bf16 v[68:71], v[176:179], v[222:225], v[68:71]
	v_mfma_f32_16x16x32_bf16 v[64:67], v[190:193], v[222:225], v[64:67]
	s_setprio 0
	s_barrier
	s_add_u32 s98, s24, s8
	s_addc_u32 s99, s25, s9
	s_add_u32 s100, s26, s8
	s_addc_u32 s101, s27, s9
	s_add_i32 s54, s54, s31
	s_mov_b32 m0, s54
	ds_read_b128 v[194:197], v155 offset:16384
	ds_read_b128 v[198:201], v155 offset:17408
	ds_read_b128 v[202:205], v155 offset:18432
	ds_read_b128 v[206:209], v155 offset:19456
	ds_read_b128 v[210:213], v155 offset:20480
	ds_read_b128 v[214:217], v155 offset:21504
	ds_read_b128 v[218:221], v155 offset:22528
	ds_read_b128 v[222:225], v155 offset:23552
	global_load_lds_dwordx4 v130, s[24:25]
	s_add_i32 m0, s54, 0x2000
	s_add_u32 s54, s24, 0x40000
	s_addc_u32 s55, s25, 0
	s_add_i32 s76, s43, s31
	global_load_lds_dwordx4 v134, s[24:25]
	s_mov_b32 m0, s76
	s_nop 0
	global_load_lds_dwordx4 v130, s[54:55]
	s_add_i32 m0, s76, 0x2000
	s_nop 0
	global_load_lds_dwordx4 v134, s[54:55]
	s_mov_b32 m0, s13
	s_nop 0
	global_load_lds_dwordx4 v128, s[26:27]
	s_mov_b32 m0, s34
	s_nop 0
	global_load_lds_dwordx4 v132, s[26:27]
	s_waitcnt vmcnt(8)
	s_waitcnt lgkmcnt(0)
	s_barrier
	s_setprio 1
	v_mfma_f32_16x16x32_bf16 v[60:63], v[156:159], v[194:197], 0
	v_mfma_f32_16x16x32_bf16 v[56:59], v[164:167], v[194:197], 0
	v_mfma_f32_16x16x32_bf16 v[52:55], v[156:159], v[202:205], 0
	v_mfma_f32_16x16x32_bf16 v[48:51], v[164:167], v[202:205], 0
	v_mfma_f32_16x16x32_bf16 v[36:39], v[156:159], v[210:213], 0
	v_mfma_f32_16x16x32_bf16 v[32:35], v[164:167], v[210:213], 0
	v_mfma_f32_16x16x32_bf16 v[20:23], v[156:159], v[218:221], 0
	v_mfma_f32_16x16x32_bf16 v[16:19], v[164:167], v[218:221], 0
	v_mfma_f32_16x16x32_bf16 v[60:63], v[160:163], v[198:201], v[60:63]
	v_mfma_f32_16x16x32_bf16 v[56:59], v[168:171], v[198:201], v[56:59]
	v_mfma_f32_16x16x32_bf16 v[52:55], v[160:163], v[206:209], v[52:55]
	v_mfma_f32_16x16x32_bf16 v[48:51], v[168:171], v[206:209], v[48:51]
	v_mfma_f32_16x16x32_bf16 v[36:39], v[160:163], v[214:217], v[36:39]
	v_mfma_f32_16x16x32_bf16 v[32:35], v[168:171], v[214:217], v[32:35]
	v_mfma_f32_16x16x32_bf16 v[20:23], v[160:163], v[222:225], v[20:23]
	v_mfma_f32_16x16x32_bf16 v[16:19], v[168:171], v[222:225], v[16:19]
	v_mfma_f32_16x16x32_bf16 v[44:47], v[172:175], v[194:197], 0
	v_mfma_f32_16x16x32_bf16 v[40:43], v[182:185], v[194:197], 0
	v_mfma_f32_16x16x32_bf16 v[28:31], v[172:175], v[202:205], 0
	v_mfma_f32_16x16x32_bf16 v[24:27], v[182:185], v[202:205], 0
	v_mfma_f32_16x16x32_bf16 v[12:15], v[172:175], v[210:213], 0
	v_mfma_f32_16x16x32_bf16 v[8:11], v[182:185], v[210:213], 0
	v_mfma_f32_16x16x32_bf16 v[4:7], v[172:175], v[218:221], 0
	v_mfma_f32_16x16x32_bf16 v[0:3], v[182:185], v[218:221], 0
	v_mfma_f32_16x16x32_bf16 v[44:47], v[176:179], v[198:201], v[44:47]
	v_mfma_f32_16x16x32_bf16 v[40:43], v[190:193], v[198:201], v[40:43]
	v_mfma_f32_16x16x32_bf16 v[28:31], v[176:179], v[206:209], v[28:31]
	v_mfma_f32_16x16x32_bf16 v[24:27], v[190:193], v[206:209], v[24:27]
	v_mfma_f32_16x16x32_bf16 v[12:15], v[176:179], v[214:217], v[12:15]
	v_mfma_f32_16x16x32_bf16 v[8:11], v[190:193], v[214:217], v[8:11]
	v_mfma_f32_16x16x32_bf16 v[4:7], v[176:179], v[222:225], v[4:7]
	v_mfma_f32_16x16x32_bf16 v[0:3], v[190:193], v[222:225], v[0:3]
	s_setprio 0
	s_barrier
	s_branch .Lmy_peel_150_mid
; #define PG8_STAGE(bufoff, gbase, voff) do { _Pragma("unroll") for (int _i = 0; _i < 2; ++_i) \
;         __builtin_amdgcn_global_load_lds((const unsigned*)((const char*)(gbase) + (voff)[_i]), (PG8_LAS unsigned*)(lds + (bufoff) + ldsw + _i * 8192), 16, 0, 0); } while (0)
; #define PG8_LDA(dst, b, h) do { _Pragma("unroll") for (int m = 0; m < 4; ++m) _Pragma("unroll") for (int k = 0; k < 2; ++k) dst[m][k] = *(const PG8_LAS bf16x8*)(lds + PG8_SA(b, h) + aoff + m * 2048 + k * 1024); } while (0)
; #define PG8_LDB(dst, b, h) do { _Pragma("unroll") for (int n = 0; n < 2; ++n) _Pragma("unroll") for (int k = 0; k < 2; ++k) dst[n][k] = *(const PG8_LAS bf16x8*)(lds + PG8_SB(b, h) + boff + n * 2048 + k * 1024); } while (0)
; #define PG8_MMA(ai, bj, At, Bt) do { __builtin_amdgcn_s_setprio(1); _Pragma("unroll") for (int m = 0; m < 4; ++m) _Pragma("unroll") for (int n = 0; n < 2; ++n) _Pragma("unroll") for (int k = 0; k < 2; ++k) \
;         acc[ai][bj][m][n] = __builtin_amdgcn_mfma_f32_16x16x32_bf16(Bt[n][k], At[m][k], acc[ai][bj][m][n], 0, 0, 0); __builtin_amdgcn_s_setprio(0); } while (0)
; #define PG8_WAIT_V(n) asm volatile("s_waitcnt vmcnt(" #n ")" ::: "memory")
; #define PG8_WAIT_L(n) asm volatile("s_waitcnt lgkmcnt(" #n ")" ::: "memory")
; #define PG8_BAR __builtin_amdgcn_s_barrier()
; #define PG8_SCHED __builtin_amdgcn_sched_barrier(0)
; template <class Epi, class Sched, bool ALIGN_EPI = false, bool SP2 = false>
; __device__ __forceinline__ void gemm_phase(PG8_LAS unsigned char* lds, const Gemm g, const Sched& S, const Epi& E) {
;     ...
;             PG8_LDB(B0, 0, 0); PG8_LDB(B1, 0, 1); PG8_SCHED; PG8_LDA(At, 0, 0); PG8_STAGE(PG8_SA(1, 1), a1 + hstep, voffA);
;             PG8_WAIT_V(8); PG8_WAIT_L(0); PG8_BAR; PG8_MMA(0, 0, At, B0); PG8_MMA(0, 1, At, B1); PG8_BAR; PG8_SCHED;
;             PG8_LDA(At, 0, 1); PG8_STAGE(PG8_SB(0, 0), b2, voffB); PG8_STAGE(PG8_SB(0, 1), b2 + hstep, voffB); PG8_STAGE(PG8_SA(0, 0), a2, voffA);
;             PG8_WAIT_V(8); PG8_WAIT_L(0); PG8_BAR; PG8_MMA(1, 0, At, B0); PG8_MMA(1, 1, At, B1); PG8_BAR; PG8_SCHED;
.LBB0_150:
	s_add_u32 s24, s22, 0xfffc0080
	s_addc_u32 s25, s23, -1
	s_waitcnt lgkmcnt(0)
	s_add_i32 s54, 0, 0x10000
	v_add_u32_e32 v147, s54, v152
	ds_read_b128 v[156:159], v147
	ds_read_b128 v[160:163], v147 offset:1024
	ds_read_b128 v[164:167], v147 offset:2048
	ds_read_b128 v[168:171], v147 offset:3072
	ds_read_b128 v[172:175], v154
	ds_read_b128 v[176:179], v154 offset:1024
	ds_read_b128 v[182:185], v154 offset:2048
	ds_read_b128 v[190:193], v154 offset:3072
	s_cmp_eq_u32 s49, 12
	s_cselect_b32 s27, s17, s25
	s_cselect_b32 s26, s45, s24
	s_cselect_b32 s25, s15, s48
	s_cselect_b32 s24, s46, s47
	s_add_i32 m0, s13, 0xc000
	ds_read_b128 v[194:197], v155
	ds_read_b128 v[198:201], v155 offset:1024
	ds_read_b128 v[202:205], v155 offset:2048
	ds_read_b128 v[206:209], v155 offset:3072
	ds_read_b128 v[210:213], v155 offset:4096
	ds_read_b128 v[214:217], v155 offset:5120
	ds_read_b128 v[218:221], v155 offset:6144
	ds_read_b128 v[222:225], v155 offset:7168
	global_load_lds_dwordx4 v138, s[22:23]
	s_add_i32 m0, s13, 0xe000
	s_nop 0
	global_load_lds_dwordx4 v140, s[22:23]
	s_waitcnt vmcnt(8)
	s_waitcnt lgkmcnt(0)
	s_barrier
	s_setprio 1
	v_mfma_f32_16x16x32_bf16 v[124:127], v[156:159], v[194:197], v[124:127]
	v_mfma_f32_16x16x32_bf16 v[120:123], v[164:167], v[194:197], v[120:123]
	v_mfma_f32_16x16x32_bf16 v[116:119], v[156:159], v[202:205], v[116:119]
	v_mfma_f32_16x16x32_bf16 v[112:115], v[164:167], v[202:205], v[112:115]
	v_mfma_f32_16x16x32_bf16 v[100:103], v[156:159], v[210:213], v[100:103]
	v_mfma_f32_16x16x32_bf16 v[96:99], v[164:167], v[210:213], v[96:99]
	v_mfma_f32_16x16x32_bf16 v[84:87], v[156:159], v[218:221], v[84:87]
	v_mfma_f32_16x16x32_bf16 v[80:83], v[164:167], v[218:221], v[80:83]
	v_mfma_f32_16x16x32_bf16 v[124:127], v[160:163], v[198:201], v[124:127]
	v_mfma_f32_16x16x32_bf16 v[120:123], v[168:171], v[198:201], v[120:123]
	v_mfma_f32_16x16x32_bf16 v[116:119], v[160:163], v[206:209], v[116:119]
	v_mfma_f32_16x16x32_bf16 v[112:115], v[168:171], v[206:209], v[112:115]
	v_mfma_f32_16x16x32_bf16 v[100:103], v[160:163], v[214:217], v[100:103]
	v_mfma_f32_16x16x32_bf16 v[96:99], v[168:171], v[214:217], v[96:99]
	v_mfma_f32_16x16x32_bf16 v[84:87], v[160:163], v[222:225], v[84:87]
	v_mfma_f32_16x16x32_bf16 v[80:83], v[168:171], v[222:225], v[80:83]
	v_mfma_f32_16x16x32_bf16 v[108:111], v[172:175], v[194:197], v[108:111]
	v_mfma_f32_16x16x32_bf16 v[104:107], v[182:185], v[194:197], v[104:107]
	v_mfma_f32_16x16x32_bf16 v[92:95], v[172:175], v[202:205], v[92:95]
	v_mfma_f32_16x16x32_bf16 v[88:91], v[182:185], v[202:205], v[88:91]
	v_mfma_f32_16x16x32_bf16 v[76:79], v[172:175], v[210:213], v[76:79]
	v_mfma_f32_16x16x32_bf16 v[72:75], v[182:185], v[210:213], v[72:75]
	v_mfma_f32_16x16x32_bf16 v[68:71], v[172:175], v[218:221], v[68:71]
	v_mfma_f32_16x16x32_bf16 v[64:67], v[182:185], v[218:221], v[64:67]
	v_mfma_f32_16x16x32_bf16 v[108:111], v[176:179], v[198:201], v[108:111]
	v_mfma_f32_16x16x32_bf16 v[104:107], v[190:193], v[198:201], v[104:107]
	v_mfma_f32_16x16x32_bf16 v[92:95], v[176:179], v[206:209], v[92:95]
	v_mfma_f32_16x16x32_bf16 v[88:91], v[190:193], v[206:209], v[88:91]
	v_mfma_f32_16x16x32_bf16 v[76:79], v[176:179], v[214:217], v[76:79]
	v_mfma_f32_16x16x32_bf16 v[72:75], v[190:193], v[214:217], v[72:75]
	v_mfma_f32_16x16x32_bf16 v[68:71], v[176:179], v[222:225], v[68:71]
	v_mfma_f32_16x16x32_bf16 v[64:67], v[190:193], v[222:225], v[64:67]
	s_setprio 0
	s_barrier
	s_add_u32 s98, s24, s8
	s_addc_u32 s99, s25, s9
	s_add_u32 s100, s26, s8
	s_addc_u32 s101, s27, s9
	s_add_i32 s54, s54, s31
	s_mov_b32 m0, s54
	ds_read_b128 v[194:197], v155 offset:16384
	ds_read_b128 v[198:201], v155 offset:17408
	ds_read_b128 v[202:205], v155 offset:18432
	ds_read_b128 v[206:209], v155 offset:19456
	ds_read_b128 v[210:213], v155 offset:20480
	ds_read_b128 v[214:217], v155 offset:21504
	ds_read_b128 v[218:221], v155 offset:22528
	ds_read_b128 v[222:225], v155 offset:23552
	global_load_lds_dwordx4 v130, s[24:25]
	s_add_i32 m0, s54, 0x2000
	s_add_u32 s54, s24, 0x40000
	s_addc_u32 s55, s25, 0
	s_add_i32 s76, s43, s31
	global_load_lds_dwordx4 v134, s[24:25]
	s_mov_b32 m0, s76
	s_nop 0
	global_load_lds_dwordx4 v130, s[54:55]
	s_add_i32 m0, s76, 0x2000
	s_nop 0
	global_load_lds_dwordx4 v134, s[54:55]
	s_mov_b32 m0, s13
	s_nop 0
	global_load_lds_dwordx4 v128, s[26:27]
	s_mov_b32 m0, s34
	s_nop 0
	global_load_lds_dwordx4 v132, s[26:27]
	s_waitcnt vmcnt(8)
	s_waitcnt lgkmcnt(0)
	s_barrier
	s_setprio 1
	v_mfma_f32_16x16x32_bf16 v[60:63], v[156:159], v[194:197], v[60:63]
	v_mfma_f32_16x16x32_bf16 v[56:59], v[164:167], v[194:197], v[56:59]
	v_mfma_f32_16x16x32_bf16 v[52:55], v[156:159], v[202:205], v[52:55]
	v_mfma_f32_16x16x32_bf16 v[48:51], v[164:167], v[202:205], v[48:51]
	v_mfma_f32_16x16x32_bf16 v[36:39], v[156:159], v[210:213], v[36:39]
	v_mfma_f32_16x16x32_bf16 v[32:35], v[164:167], v[210:213], v[32:35]
	v_mfma_f32_16x16x32_bf16 v[20:23], v[156:159], v[218:221], v[20:23]
	v_mfma_f32_16x16x32_bf16 v[16:19], v[164:167], v[218:221], v[16:19]
	v_mfma_f32_16x16x32_bf16 v[60:63], v[160:163], v[198:201], v[60:63]
	v_mfma_f32_16x16x32_bf16 v[56:59], v[168:171], v[198:201], v[56:59]
	v_mfma_f32_16x16x32_bf16 v[52:55], v[160:163], v[206:209], v[52:55]
	v_mfma_f32_16x16x32_bf16 v[48:51], v[168:171], v[206:209], v[48:51]
	v_mfma_f32_16x16x32_bf16 v[36:39], v[160:163], v[214:217], v[36:39]
	v_mfma_f32_16x16x32_bf16 v[32:35], v[168:171], v[214:217], v[32:35]
	v_mfma_f32_16x16x32_bf16 v[20:23], v[160:163], v[222:225], v[20:23]
	v_mfma_f32_16x16x32_bf16 v[16:19], v[168:171], v[222:225], v[16:19]
	v_mfma_f32_16x16x32_bf16 v[44:47], v[172:175], v[194:197], v[44:47]
	v_mfma_f32_16x16x32_bf16 v[40:43], v[182:185], v[194:197], v[40:43]
	v_mfma_f32_16x16x32_bf16 v[28:31], v[172:175], v[202:205], v[28:31]
	v_mfma_f32_16x16x32_bf16 v[24:27], v[182:185], v[202:205], v[24:27]
	v_mfma_f32_16x16x32_bf16 v[12:15], v[172:175], v[210:213], v[12:15]
	v_mfma_f32_16x16x32_bf16 v[8:11], v[182:185], v[210:213], v[8:11]
	v_mfma_f32_16x16x32_bf16 v[4:7], v[172:175], v[218:221], v[4:7]
	v_mfma_f32_16x16x32_bf16 v[0:3], v[182:185], v[218:221], v[0:3]
	v_mfma_f32_16x16x32_bf16 v[44:47], v[176:179], v[198:201], v[44:47]
	v_mfma_f32_16x16x32_bf16 v[40:43], v[190:193], v[198:201], v[40:43]
	v_mfma_f32_16x16x32_bf16 v[28:31], v[176:179], v[206:209], v[28:31]
	v_mfma_f32_16x16x32_bf16 v[24:27], v[190:193], v[206:209], v[24:27]
	v_mfma_f32_16x16x32_bf16 v[12:15], v[176:179], v[214:217], v[12:15]
	v_mfma_f32_16x16x32_bf16 v[8:11], v[190:193], v[214:217], v[8:11]
	v_mfma_f32_16x16x32_bf16 v[4:7], v[176:179], v[222:225], v[4:7]
	v_mfma_f32_16x16x32_bf16 v[0:3], v[190:193], v[222:225], v[0:3]
	s_setprio 0
	s_barrier
; #define PG8_STAGE(bufoff, gbase, voff) do { _Pragma("unroll") for (int _i = 0; _i < 2; ++_i) \
;         __builtin_amdgcn_global_load_lds((const unsigned*)((const char*)(gbase) + (voff)[_i]), (PG8_LAS unsigned*)(lds + (bufoff) + ldsw + _i * 8192), 16, 0, 0); } while (0)
; #define PG8_LDA(dst, b, h) do { _Pragma("unroll") for (int m = 0; m < 4; ++m) _Pragma("unroll") for (int k = 0; k < 2; ++k) dst[m][k] = *(const PG8_LAS bf16x8*)(lds + PG8_SA(b, h) + aoff + m * 2048 + k * 1024); } while (0)
; #define PG8_LDB(dst, b, h) do { _Pragma("unroll") for (int n = 0; n < 2; ++n) _Pragma("unroll") for (int k = 0; k < 2; ++k) dst[n][k] = *(const PG8_LAS bf16x8*)(lds + PG8_SB(b, h) + boff + n * 2048 + k * 1024); } while (0)
; #define PG8_MMA(ai, bj, At, Bt) do { __builtin_amdgcn_s_setprio(1); _Pragma("unroll") for (int m = 0; m < 4; ++m) _Pragma("unroll") for (int n = 0; n < 2; ++n) _Pragma("unroll") for (int k = 0; k < 2; ++k) \
;         acc[ai][bj][m][n] = __builtin_amdgcn_mfma_f32_16x16x32_bf16(Bt[n][k], At[m][k], acc[ai][bj][m][n], 0, 0, 0); __builtin_amdgcn_s_setprio(0); } while (0)
; #define PG8_WAIT_V(n) asm volatile("s_waitcnt vmcnt(" #n ")" ::: "memory")
; #define PG8_WAIT_L(n) asm volatile("s_waitcnt lgkmcnt(" #n ")" ::: "memory")
; #define PG8_BAR __builtin_amdgcn_s_barrier()
; #define PG8_SCHED __builtin_amdgcn_sched_barrier(0)
; template <class Epi, class Sched, bool ALIGN_EPI = false, bool SP2 = false>
; __device__ __forceinline__ void gemm_phase(PG8_LAS unsigned char* lds, const Gemm g, const Sched& S, const Epi& E) {
;     ...
;         for (int t = 0; t < nt; t += 2) {
;             const bool last = (t == nt - 2);
;             const char* a1 = cA + (size_t)(t + 1) * kstep;
;             const char* a2 = last ? nA : cA + (size_t)(t + 2) * kstep; const char* b2 = last ? nB : cB + (size_t)(t + 2) * kstep;
;     ...
;             PG8_LDB(B0, 1, 0); PG8_LDB(B1, 1, 1); PG8_SCHED; PG8_LDA(At, 1, 0); PG8_STAGE(PG8_SA(0, 1), a2 + hstep, voffA);
;             PG8_WAIT_V(8); PG8_WAIT_L(0); PG8_BAR; PG8_MMA(0, 0, At, B0); PG8_MMA(0, 1, At, B1); PG8_BAR; PG8_SCHED;
;             PG8_LDA(At, 1, 1); PG8_STAGE(PG8_SB(1, 0), b3, voffB); PG8_STAGE(PG8_SB(1, 1), b3 + hstep, voffB); PG8_STAGE(PG8_SA(1, 0), a3, voffA);
;             PG8_WAIT_V(8); PG8_WAIT_L(0); PG8_BAR; PG8_MMA(1, 0, At, B0); PG8_MMA(1, 1, At, B1); PG8_BAR; PG8_SCHED;
.Lmy_peel_150_mid:
	s_add_i32 s54, 0, 0x18000
	v_add_u32_e32 v147, s54, v152
	s_add_i32 s55, 0, 0x1c000
	ds_read_b128 v[156:159], v147
	ds_read_b128 v[160:163], v147 offset:1024
	ds_read_b128 v[164:167], v147 offset:2048
	ds_read_b128 v[168:171], v147 offset:3072
	v_add_u32_e32 v147, s55, v152
	ds_read_b128 v[172:175], v147
	ds_read_b128 v[176:179], v147 offset:1024
	ds_read_b128 v[182:185], v147 offset:2048
	ds_read_b128 v[190:193], v147 offset:3072
	s_add_u32 s26, s26, 0x40000
	s_addc_u32 s27, s27, 0
	s_mov_b32 m0, s35
	ds_read_b128 v[194:197], v155 offset:32768
	ds_read_b128 v[198:201], v155 offset:33792
	ds_read_b128 v[202:205], v155 offset:34816
	ds_read_b128 v[206:209], v155 offset:35840
	ds_read_b128 v[210:213], v155 offset:36864
	ds_read_b128 v[214:217], v155 offset:37888
	ds_read_b128 v[218:221], v155 offset:38912
	ds_read_b128 v[222:225], v155 offset:39936
	global_load_lds_dwordx4 v128, s[26:27]
	s_mov_b32 m0, s36
	s_nop 0
	global_load_lds_dwordx4 v132, s[26:27]
	s_waitcnt vmcnt(8)
	s_waitcnt lgkmcnt(0)
	s_barrier
	s_setprio 1
	v_mfma_f32_16x16x32_bf16 v[124:127], v[156:159], v[194:197], v[124:127]
	v_mfma_f32_16x16x32_bf16 v[120:123], v[164:167], v[194:197], v[120:123]
	v_mfma_f32_16x16x32_bf16 v[116:119], v[156:159], v[202:205], v[116:119]
	v_mfma_f32_16x16x32_bf16 v[112:115], v[164:167], v[202:205], v[112:115]
	v_mfma_f32_16x16x32_bf16 v[100:103], v[156:159], v[210:213], v[100:103]
	v_mfma_f32_16x16x32_bf16 v[96:99], v[164:167], v[210:213], v[96:99]
	v_mfma_f32_16x16x32_bf16 v[84:87], v[156:159], v[218:221], v[84:87]
	v_mfma_f32_16x16x32_bf16 v[80:83], v[164:167], v[218:221], v[80:83]
	v_mfma_f32_16x16x32_bf16 v[124:127], v[160:163], v[198:201], v[124:127]
	v_mfma_f32_16x16x32_bf16 v[120:123], v[168:171], v[198:201], v[120:123]
	v_mfma_f32_16x16x32_bf16 v[116:119], v[160:163], v[206:209], v[116:119]
	v_mfma_f32_16x16x32_bf16 v[112:115], v[168:171], v[206:209], v[112:115]
	v_mfma_f32_16x16x32_bf16 v[100:103], v[160:163], v[214:217], v[100:103]
	v_mfma_f32_16x16x32_bf16 v[96:99], v[168:171], v[214:217], v[96:99]
	v_mfma_f32_16x16x32_bf16 v[84:87], v[160:163], v[222:225], v[84:87]
	v_mfma_f32_16x16x32_bf16 v[80:83], v[168:171], v[222:225], v[80:83]
	v_mfma_f32_16x16x32_bf16 v[108:111], v[172:175], v[194:197], v[108:111]
	v_mfma_f32_16x16x32_bf16 v[104:107], v[182:185], v[194:197], v[104:107]
	v_mfma_f32_16x16x32_bf16 v[92:95], v[172:175], v[202:205], v[92:95]
	v_mfma_f32_16x16x32_bf16 v[88:91], v[182:185], v[202:205], v[88:91]
	v_mfma_f32_16x16x32_bf16 v[76:79], v[172:175], v[210:213], v[76:79]
	v_mfma_f32_16x16x32_bf16 v[72:75], v[182:185], v[210:213], v[72:75]
	v_mfma_f32_16x16x32_bf16 v[68:71], v[172:175], v[218:221], v[68:71]
	v_mfma_f32_16x16x32_bf16 v[64:67], v[182:185], v[218:221], v[64:67]
	v_mfma_f32_16x16x32_bf16 v[108:111], v[176:179], v[198:201], v[108:111]
	v_mfma_f32_16x16x32_bf16 v[104:107], v[190:193], v[198:201], v[104:107]
	v_mfma_f32_16x16x32_bf16 v[92:95], v[176:179], v[206:209], v[92:95]
	v_mfma_f32_16x16x32_bf16 v[88:91], v[190:193], v[206:209], v[88:91]
	v_mfma_f32_16x16x32_bf16 v[76:79], v[176:179], v[214:217], v[76:79]
	v_mfma_f32_16x16x32_bf16 v[72:75], v[190:193], v[214:217], v[72:75]
	v_mfma_f32_16x16x32_bf16 v[68:71], v[176:179], v[222:225], v[68:71]
	v_mfma_f32_16x16x32_bf16 v[64:67], v[190:193], v[222:225], v[64:67]
	s_setprio 0
	s_barrier
	s_add_i32 s26, s54, s31
	s_mov_b32 m0, s26
	ds_read_b128 v[194:197], v155 offset:49152
	ds_read_b128 v[198:201], v155 offset:50176
	ds_read_b128 v[202:205], v155 offset:51200
	ds_read_b128 v[206:209], v155 offset:52224
	ds_read_b128 v[210:213], v155 offset:53248
	ds_read_b128 v[214:217], v155 offset:54272
	ds_read_b128 v[218:221], v155 offset:55296
	ds_read_b128 v[222:225], v155 offset:56320
	global_load_lds_dwordx4 v130, s[98:99]
	s_add_i32 m0, s26, 0x2000
	s_add_u32 s24, s24, 0x40080
	s_addc_u32 s25, s25, 0
	s_add_i32 s26, s55, s31
	global_load_lds_dwordx4 v134, s[98:99]
	s_mov_b32 m0, s26
	s_nop 0
	global_load_lds_dwordx4 v130, s[24:25]
	s_add_i32 m0, s26, 0x2000
	s_nop 0
	global_load_lds_dwordx4 v134, s[24:25]
	s_mov_b32 m0, s39
	s_nop 0
	global_load_lds_dwordx4 v128, s[100:101]
	s_mov_b32 m0, s40
	s_nop 0
	global_load_lds_dwordx4 v132, s[100:101]
	s_waitcnt vmcnt(8)
	s_waitcnt lgkmcnt(0)
	s_barrier
	s_setprio 1
	v_mfma_f32_16x16x32_bf16 v[60:63], v[156:159], v[194:197], v[60:63]
	v_mfma_f32_16x16x32_bf16 v[56:59], v[164:167], v[194:197], v[56:59]
	v_mfma_f32_16x16x32_bf16 v[52:55], v[156:159], v[202:205], v[52:55]
	v_mfma_f32_16x16x32_bf16 v[48:51], v[164:167], v[202:205], v[48:51]
	v_mfma_f32_16x16x32_bf16 v[36:39], v[156:159], v[210:213], v[36:39]
	v_mfma_f32_16x16x32_bf16 v[32:35], v[164:167], v[210:213], v[32:35]
	v_mfma_f32_16x16x32_bf16 v[20:23], v[156:159], v[218:221], v[20:23]
	v_mfma_f32_16x16x32_bf16 v[16:19], v[164:167], v[218:221], v[16:19]
	v_mfma_f32_16x16x32_bf16 v[60:63], v[160:163], v[198:201], v[60:63]
	v_mfma_f32_16x16x32_bf16 v[56:59], v[168:171], v[198:201], v[56:59]
	v_mfma_f32_16x16x32_bf16 v[52:55], v[160:163], v[206:209], v[52:55]
	v_mfma_f32_16x16x32_bf16 v[48:51], v[168:171], v[206:209], v[48:51]
	v_mfma_f32_16x16x32_bf16 v[36:39], v[160:163], v[214:217], v[36:39]
	v_mfma_f32_16x16x32_bf16 v[32:35], v[168:171], v[214:217], v[32:35]
	v_mfma_f32_16x16x32_bf16 v[20:23], v[160:163], v[222:225], v[20:23]
	v_mfma_f32_16x16x32_bf16 v[16:19], v[168:171], v[222:225], v[16:19]
	v_mfma_f32_16x16x32_bf16 v[44:47], v[172:175], v[194:197], v[44:47]
	v_mfma_f32_16x16x32_bf16 v[40:43], v[182:185], v[194:197], v[40:43]
	v_mfma_f32_16x16x32_bf16 v[28:31], v[172:175], v[202:205], v[28:31]
	v_mfma_f32_16x16x32_bf16 v[24:27], v[182:185], v[202:205], v[24:27]
	v_mfma_f32_16x16x32_bf16 v[12:15], v[172:175], v[210:213], v[12:15]
	v_mfma_f32_16x16x32_bf16 v[8:11], v[182:185], v[210:213], v[8:11]
	v_mfma_f32_16x16x32_bf16 v[4:7], v[172:175], v[218:221], v[4:7]
	v_mfma_f32_16x16x32_bf16 v[0:3], v[182:185], v[218:221], v[0:3]
	v_mfma_f32_16x16x32_bf16 v[44:47], v[176:179], v[198:201], v[44:47]
	v_mfma_f32_16x16x32_bf16 v[40:43], v[190:193], v[198:201], v[40:43]
	v_mfma_f32_16x16x32_bf16 v[28:31], v[176:179], v[206:209], v[28:31]
	v_mfma_f32_16x16x32_bf16 v[24:27], v[190:193], v[206:209], v[24:27]
	v_mfma_f32_16x16x32_bf16 v[12:15], v[176:179], v[214:217], v[12:15]
	v_mfma_f32_16x16x32_bf16 v[8:11], v[190:193], v[214:217], v[8:11]
	v_mfma_f32_16x16x32_bf16 v[4:7], v[176:179], v[222:225], v[4:7]
	v_mfma_f32_16x16x32_bf16 v[0:3], v[190:193], v[222:225], v[0:3]
	s_setprio 0
	s_barrier
	s_add_i32 s49, s49, 2
	s_add_u32 s22, s22, 0x100
	s_addc_u32 s23, s23, 0
	s_add_u32 s47, s47, 0x100
	s_addc_u32 s48, s48, 0
	s_cmp_gt_u32 s49, 13
	s_cbranch_scc0 .LBB0_150
	s_and_b64 vcc, exec, s[10:11]
	s_cbranch_vccz .LBB0_153
	s_barrier

;     __host__ __device__ bool next(int i, Unit& u) const { const long L = (long)i * G + c; if (L >= nwg) return false; return unit_of((int)L, u); }
;     __host__ __device__ bool next(int i, Unit& u) const { const int L = i == 0 ? l0 : (i == 1 ? l1 : (i == 2 ? l2 : -1)); if (L < 0 || L >= s.nwg) return false; return s.unit_of(L, u); }
;     __host__ __device__ bool next(int i, Unit& u) const { const bool ok = s.next(i >> 1, u); u.kh = i & 1; return ok; }
; #define PG8_STAGE(bufoff, gbase, voff) do { _Pragma("unroll") for (int _i = 0; _i < 2; ++_i) \
;         __builtin_amdgcn_global_load_lds((const unsigned*)((const char*)(gbase) + (voff)[_i]), (PG8_LAS unsigned*)(lds + (bufoff) + ldsw + _i * 8192), 16, 0, 0); } while (0)
; #define PG8_LDA(dst, b, h) do { _Pragma("unroll") for (int m = 0; m < 4; ++m) _Pragma("unroll") for (int k = 0; k < 2; ++k) dst[m][k] = *(const PG8_LAS bf16x8*)(lds + PG8_SA(b, h) + aoff + m * 2048 + k * 1024); } while (0)
; template <class Epi, class Sched, bool ALIGN_EPI = false, bool SP2 = false>
; __device__ __forceinline__ void gemm_phase(PG8_LAS unsigned char* lds, const Gemm g, const Sched& S, const Epi& E) {
;     ...
;         const bool has_next = S.next(ui + 1, nxt);
;         const char* nA = has_next ? (const char*)g.A + (size_t)nxt.pm * tstep + nxt.kh * khb : cA; const char* nB = has_next ? (const char*)g.Bt + (size_t)nxt.pn * tstep + nxt.kh * khb : cB;
;         for (int t = 0; t < nt; t += 2) {
;             const bool last = (t == nt - 2);
;             const char* a1 = cA + (size_t)(t + 1) * kstep;
;             const char* a2 = last ? nA : cA + (size_t)(t + 2) * kstep; const char* b2 = last ? nB : cB + (size_t)(t + 2) * kstep;
;             const char* a3 = a2 + kstep; const char* b3 = b2 + kstep;
;             if (last && has_next) S.a_ready(nxt);
;             if constexpr (SP2) {
;             PG8_LDB(B0, 0, 0); PG8_LDB(B1, 0, 1); PG8_SCHED; PG8_LDA(At, 0, 0); PG8_STAGE(PG8_SA(1, 1), a1 + hstep, voffA);
;             PG8_WAIT_V(8); PG8_WAIT_L(0); PG8_BAR; PG8_MMA(0, 0, At, B0); PG8_MMA(0, 1, At, B1); PG8_BAR; PG8_SCHED;
;             PG8_LDA(At, 0, 1); PG8_STAGE(PG8_SB(0, 0), b2, voffB); PG8_STAGE(PG8_SB(0, 1), b2 + hstep, voffB); PG8_STAGE(PG8_SA(0, 0), a2, voffA);
;             PG8_WAIT_V(8); PG8_WAIT_L(0); PG8_BAR; PG8_MMA(1, 0, At, B0); PG8_MMA(1, 1, At, B1); PG8_BAR; PG8_SCHED;
.LBB0_683:
	s_ashr_i32 s3, s2, 31
	s_lshl_b64 s[12:13], s[2:3], 19
	v_readlane_b32 s3, v254, 13
	s_add_u32 s16, s3, s12
	v_readlane_b32 s3, v254, 17
	s_addc_u32 s17, s3, s13
	s_and_b64 s[12:13], s[38:39], exec
	s_cselect_b32 s3, s17, s1
	s_cselect_b32 s94, s16, s0
	s_ashr_i32 s5, s4, 31
	s_lshl_b64 s[12:13], s[4:5], 19
	v_readlane_b32 s5, v254, 15
	s_add_u32 s12, s5, s12
	s_addc_u32 s13, s50, s13
	s_and_b64 s[42:43], s[38:39], exec
	s_cselect_b32 s5, s13, s41
	s_cselect_b32 s95, s12, s40
	s_add_u32 s0, s0, 0x40080
	s_addc_u32 s1, s1, 0
	s_add_u32 s96, s40, 0x100
	s_addc_u32 s97, s41, 0
	s_mov_b32 vcc_lo, -2
	ds_read_b128 v[128:131], v174
	ds_read_b128 v[132:135], v174 offset:1024
	ds_read_b128 v[136:139], v174 offset:2048
	ds_read_b128 v[140:143], v174 offset:3072
	ds_read_b128 v[162:165], v175
	ds_read_b128 v[166:169], v175 offset:1024
	ds_read_b128 v[180:183], v175 offset:2048
	ds_read_b128 v[184:187], v175 offset:3072
	s_add_u32 s8, s0, 0xfffc0080
	s_addc_u32 s9, s1, -1
	s_cmp_eq_u32 vcc_lo, 12
	s_cselect_b32 s43, s3, s9
	s_cselect_b32 s42, s94, s8
	s_cselect_b32 s41, s5, s97
	s_cselect_b32 s40, s95, s96
	s_add_i32 m0, s47, 0xc000
	ds_read_b128 v[190:193], v176
	ds_read_b128 v[194:197], v176 offset:1024
	ds_read_b128 v[198:201], v176 offset:2048
	ds_read_b128 v[202:205], v176 offset:3072
	ds_read_b128 v[206:209], v176 offset:4096
	ds_read_b128 v[210:213], v176 offset:5120
	ds_read_b128 v[214:217], v176 offset:6144
	ds_read_b128 v[218:221], v176 offset:7168
	global_load_lds_dwordx4 v158, s[0:1]
	s_add_i32 m0, s47, 0xe000
	s_nop 0
	global_load_lds_dwordx4 v160, s[0:1]
	s_waitcnt vmcnt(8)
	s_waitcnt lgkmcnt(0)
	s_barrier
	s_setprio 1
	v_mfma_f32_16x16x32_bf16 v[124:127], v[128:131], v[190:193], 0
	v_mfma_f32_16x16x32_bf16 v[120:123], v[136:139], v[190:193], 0
	v_mfma_f32_16x16x32_bf16 v[108:111], v[128:131], v[198:201], 0
	v_mfma_f32_16x16x32_bf16 v[104:107], v[136:139], v[198:201], 0
	v_mfma_f32_16x16x32_bf16 v[92:95], v[128:131], v[206:209], 0
	v_mfma_f32_16x16x32_bf16 v[88:91], v[136:139], v[206:209], 0
	v_mfma_f32_16x16x32_bf16 v[76:79], v[128:131], v[214:217], 0
	v_mfma_f32_16x16x32_bf16 v[72:75], v[136:139], v[214:217], 0
	v_mfma_f32_16x16x32_bf16 v[124:127], v[132:135], v[194:197], v[124:127]
	v_mfma_f32_16x16x32_bf16 v[120:123], v[140:143], v[194:197], v[120:123]
	v_mfma_f32_16x16x32_bf16 v[108:111], v[132:135], v[202:205], v[108:111]
	v_mfma_f32_16x16x32_bf16 v[104:107], v[140:143], v[202:205], v[104:107]
	v_mfma_f32_16x16x32_bf16 v[92:95], v[132:135], v[210:213], v[92:95]
	v_mfma_f32_16x16x32_bf16 v[88:91], v[140:143], v[210:213], v[88:91]
	v_mfma_f32_16x16x32_bf16 v[76:79], v[132:135], v[218:221], v[76:79]
	v_mfma_f32_16x16x32_bf16 v[72:75], v[140:143], v[218:221], v[72:75]
	v_mfma_f32_16x16x32_bf16 v[116:119], v[162:165], v[190:193], 0
	v_mfma_f32_16x16x32_bf16 v[112:115], v[180:183], v[190:193], 0
	v_mfma_f32_16x16x32_bf16 v[100:103], v[162:165], v[198:201], 0
	v_mfma_f32_16x16x32_bf16 v[96:99], v[180:183], v[198:201], 0
	v_mfma_f32_16x16x32_bf16 v[84:87], v[162:165], v[206:209], 0
	v_mfma_f32_16x16x32_bf16 v[80:83], v[180:183], v[206:209], 0
	v_mfma_f32_16x16x32_bf16 v[68:71], v[162:165], v[214:217], 0
	v_mfma_f32_16x16x32_bf16 v[64:67], v[180:183], v[214:217], 0
	v_mfma_f32_16x16x32_bf16 v[116:119], v[166:169], v[194:197], v[116:119]
	v_mfma_f32_16x16x32_bf16 v[112:115], v[184:187], v[194:197], v[112:115]
	v_mfma_f32_16x16x32_bf16 v[100:103], v[166:169], v[202:205], v[100:103]
	v_mfma_f32_16x16x32_bf16 v[96:99], v[184:187], v[202:205], v[96:99]
	v_mfma_f32_16x16x32_bf16 v[84:87], v[166:169], v[210:213], v[84:87]
	v_mfma_f32_16x16x32_bf16 v[80:83], v[184:187], v[210:213], v[80:83]
	v_mfma_f32_16x16x32_bf16 v[68:71], v[166:169], v[218:221], v[68:71]
	v_mfma_f32_16x16x32_bf16 v[64:67], v[184:187], v[218:221], v[64:67]
	s_setprio 0
	s_barrier
	s_add_u32 s98, s40, s14
	s_addc_u32 s99, s41, s15
	s_add_u32 s100, s42, s14
	s_addc_u32 s101, s43, s15
	s_add_i32 s8, s76, s46
	s_mov_b32 m0, s8
	ds_read_b128 v[190:193], v176 offset:16384
	ds_read_b128 v[194:197], v176 offset:17408
	ds_read_b128 v[198:201], v176 offset:18432
	ds_read_b128 v[202:205], v176 offset:19456
	ds_read_b128 v[206:209], v176 offset:20480
	ds_read_b128 v[210:213], v176 offset:21504
	ds_read_b128 v[214:217], v176 offset:22528
	ds_read_b128 v[218:221], v176 offset:23552
	global_load_lds_dwordx4 v146, s[40:41]
	s_add_i32 m0, s8, 0x2000
	s_add_u32 s8, s40, 0x40000
	s_addc_u32 s9, s41, 0
	s_add_i32 s54, s77, s46
	global_load_lds_dwordx4 v150, s[40:41]
	s_mov_b32 m0, s54
	s_nop 0
	global_load_lds_dwordx4 v146, s[8:9]
	s_add_i32 m0, s54, 0x2000
	s_nop 0
	global_load_lds_dwordx4 v150, s[8:9]
	s_mov_b32 m0, s47
	s_nop 0
	global_load_lds_dwordx4 v144, s[42:43]
	s_mov_b32 m0, s48
	s_nop 0
	global_load_lds_dwordx4 v148, s[42:43]
	s_waitcnt vmcnt(8)
	s_waitcnt lgkmcnt(0)
	s_barrier
	s_setprio 1
	v_mfma_f32_16x16x32_bf16 v[60:63], v[128:131], v[190:193], 0
	v_mfma_f32_16x16x32_bf16 v[56:59], v[136:139], v[190:193], 0
	v_mfma_f32_16x16x32_bf16 v[44:47], v[128:131], v[198:201], 0
	v_mfma_f32_16x16x32_bf16 v[40:43], v[136:139], v[198:201], 0
	v_mfma_f32_16x16x32_bf16 v[28:31], v[128:131], v[206:209], 0
	v_mfma_f32_16x16x32_bf16 v[24:27], v[136:139], v[206:209], 0
	v_mfma_f32_16x16x32_bf16 v[12:15], v[128:131], v[214:217], 0
	v_mfma_f32_16x16x32_bf16 v[8:11], v[136:139], v[214:217], 0
	v_mfma_f32_16x16x32_bf16 v[60:63], v[132:135], v[194:197], v[60:63]
	v_mfma_f32_16x16x32_bf16 v[56:59], v[140:143], v[194:197], v[56:59]
	v_mfma_f32_16x16x32_bf16 v[44:47], v[132:135], v[202:205], v[44:47]
	v_mfma_f32_16x16x32_bf16 v[40:43], v[140:143], v[202:205], v[40:43]
	v_mfma_f32_16x16x32_bf16 v[28:31], v[132:135], v[210:213], v[28:31]
	v_mfma_f32_16x16x32_bf16 v[24:27], v[140:143], v[210:213], v[24:27]
	v_mfma_f32_16x16x32_bf16 v[12:15], v[132:135], v[218:221], v[12:15]
	v_mfma_f32_16x16x32_bf16 v[8:11], v[140:143], v[218:221], v[8:11]
	v_mfma_f32_16x16x32_bf16 v[52:55], v[162:165], v[190:193], 0
	v_mfma_f32_16x16x32_bf16 v[48:51], v[180:183], v[190:193], 0
	v_mfma_f32_16x16x32_bf16 v[36:39], v[162:165], v[198:201], 0
	v_mfma_f32_16x16x32_bf16 v[32:35], v[180:183], v[198:201], 0
	v_mfma_f32_16x16x32_bf16 v[20:23], v[162:165], v[206:209], 0
	v_mfma_f32_16x16x32_bf16 v[16:19], v[180:183], v[206:209], 0
	v_mfma_f32_16x16x32_bf16 v[4:7], v[162:165], v[214:217], 0
	v_mfma_f32_16x16x32_bf16 v[0:3], v[180:183], v[214:217], 0
	v_mfma_f32_16x16x32_bf16 v[52:55], v[166:169], v[194:197], v[52:55]
	v_mfma_f32_16x16x32_bf16 v[48:51], v[184:187], v[194:197], v[48:51]
	v_mfma_f32_16x16x32_bf16 v[36:39], v[166:169], v[202:205], v[36:39]
	v_mfma_f32_16x16x32_bf16 v[32:35], v[184:187], v[202:205], v[32:35]
	v_mfma_f32_16x16x32_bf16 v[20:23], v[166:169], v[210:213], v[20:23]
	v_mfma_f32_16x16x32_bf16 v[16:19], v[184:187], v[210:213], v[16:19]
	v_mfma_f32_16x16x32_bf16 v[4:7], v[166:169], v[218:221], v[4:7]
	v_mfma_f32_16x16x32_bf16 v[0:3], v[184:187], v[218:221], v[0:3]
	s_setprio 0
	s_barrier
	s_branch .Lmy_peel_684_mid
; #define PG8_STAGE(bufoff, gbase, voff) do { _Pragma("unroll") for (int _i = 0; _i < 2; ++_i) \
;         __builtin_amdgcn_global_load_lds((const unsigned*)((const char*)(gbase) + (voff)[_i]), (PG8_LAS unsigned*)(lds + (bufoff) + ldsw + _i * 8192), 16, 0, 0); } while (0)
; #define PG8_LDA(dst, b, h) do { _Pragma("unroll") for (int m = 0; m < 4; ++m) _Pragma("unroll") for (int k = 0; k < 2; ++k) dst[m][k] = *(const PG8_LAS bf16x8*)(lds + PG8_SA(b, h) + aoff + m * 2048 + k * 1024); } while (0)
; #define PG8_LDB(dst, b, h) do { _Pragma("unroll") for (int n = 0; n < 2; ++n) _Pragma("unroll") for (int k = 0; k < 2; ++k) dst[n][k] = *(const PG8_LAS bf16x8*)(lds + PG8_SB(b, h) + boff + n * 2048 + k * 1024); } while (0)
; #define PG8_MMA(ai, bj, At, Bt) do { __builtin_amdgcn_s_setprio(1); _Pragma("unroll") for (int m = 0; m < 4; ++m) _Pragma("unroll") for (int n = 0; n < 2; ++n) _Pragma("unroll") for (int k = 0; k < 2; ++k) \
;         acc[ai][bj][m][n] = __builtin_amdgcn_mfma_f32_16x16x32_bf16(Bt[n][k], At[m][k], acc[ai][bj][m][n], 0, 0, 0); __builtin_amdgcn_s_setprio(0); } while (0)
; #define PG8_WAIT_V(n) asm volatile("s_waitcnt vmcnt(" #n ")" ::: "memory")
; #define PG8_WAIT_L(n) asm volatile("s_waitcnt lgkmcnt(" #n ")" ::: "memory")
; #define PG8_BAR __builtin_amdgcn_s_barrier()
; #define PG8_SCHED __builtin_amdgcn_sched_barrier(0)
; template <class Epi, class Sched, bool ALIGN_EPI = false, bool SP2 = false>
; __device__ __forceinline__ void gemm_phase(PG8_LAS unsigned char* lds, const Gemm g, const Sched& S, const Epi& E) {
;     ...
;             PG8_LDB(B0, 0, 0); PG8_LDB(B1, 0, 1); PG8_SCHED; PG8_LDA(At, 0, 0); PG8_STAGE(PG8_SA(1, 1), a1 + hstep, voffA);
;             PG8_WAIT_V(8); PG8_WAIT_L(0); PG8_BAR; PG8_MMA(0, 0, At, B0); PG8_MMA(0, 1, At, B1); PG8_BAR; PG8_SCHED;
;             PG8_LDA(At, 0, 1); PG8_STAGE(PG8_SB(0, 0), b2, voffB); PG8_STAGE(PG8_SB(0, 1), b2 + hstep, voffB); PG8_STAGE(PG8_SA(0, 0), a2, voffA);
;             PG8_WAIT_V(8); PG8_WAIT_L(0); PG8_BAR; PG8_MMA(1, 0, At, B0); PG8_MMA(1, 1, At, B1); PG8_BAR; PG8_SCHED;
.LBB0_684:
	ds_read_b128 v[128:131], v174
	ds_read_b128 v[132:135], v174 offset:1024
	ds_read_b128 v[136:139], v174 offset:2048
	ds_read_b128 v[140:143], v174 offset:3072
	ds_read_b128 v[162:165], v175
	ds_read_b128 v[166:169], v175 offset:1024
	ds_read_b128 v[180:183], v175 offset:2048
	ds_read_b128 v[184:187], v175 offset:3072
	s_add_u32 s8, s0, 0xfffc0080
	s_addc_u32 s9, s1, -1
	s_cmp_eq_u32 vcc_lo, 12
	s_cselect_b32 s43, s3, s9
	s_cselect_b32 s42, s94, s8
	s_cselect_b32 s41, s5, s97
	s_cselect_b32 s40, s95, s96
	s_add_i32 m0, s47, 0xc000
	ds_read_b128 v[190:193], v176
	ds_read_b128 v[194:197], v176 offset:1024
	ds_read_b128 v[198:201], v176 offset:2048
	ds_read_b128 v[202:205], v176 offset:3072
	ds_read_b128 v[206:209], v176 offset:4096
	ds_read_b128 v[210:213], v176 offset:5120
	ds_read_b128 v[214:217], v176 offset:6144
	ds_read_b128 v[218:221], v176 offset:7168
	global_load_lds_dwordx4 v158, s[0:1]
	s_add_i32 m0, s47, 0xe000
	s_nop 0
	global_load_lds_dwordx4 v160, s[0:1]
	s_waitcnt vmcnt(8)
	s_waitcnt lgkmcnt(0)
	s_barrier
	s_setprio 1
	v_mfma_f32_16x16x32_bf16 v[124:127], v[128:131], v[190:193], v[124:127]
	v_mfma_f32_16x16x32_bf16 v[120:123], v[136:139], v[190:193], v[120:123]
	v_mfma_f32_16x16x32_bf16 v[108:111], v[128:131], v[198:201], v[108:111]
	v_mfma_f32_16x16x32_bf16 v[104:107], v[136:139], v[198:201], v[104:107]
	v_mfma_f32_16x16x32_bf16 v[92:95], v[128:131], v[206:209], v[92:95]
	v_mfma_f32_16x16x32_bf16 v[88:91], v[136:139], v[206:209], v[88:91]
	v_mfma_f32_16x16x32_bf16 v[76:79], v[128:131], v[214:217], v[76:79]
	v_mfma_f32_16x16x32_bf16 v[72:75], v[136:139], v[214:217], v[72:75]
	v_mfma_f32_16x16x32_bf16 v[124:127], v[132:135], v[194:197], v[124:127]
	v_mfma_f32_16x16x32_bf16 v[120:123], v[140:143], v[194:197], v[120:123]
	v_mfma_f32_16x16x32_bf16 v[108:111], v[132:135], v[202:205], v[108:111]
	v_mfma_f32_16x16x32_bf16 v[104:107], v[140:143], v[202:205], v[104:107]
	v_mfma_f32_16x16x32_bf16 v[92:95], v[132:135], v[210:213], v[92:95]
	v_mfma_f32_16x16x32_bf16 v[88:91], v[140:143], v[210:213], v[88:91]
	v_mfma_f32_16x16x32_bf16 v[76:79], v[132:135], v[218:221], v[76:79]
	v_mfma_f32_16x16x32_bf16 v[72:75], v[140:143], v[218:221], v[72:75]
	v_mfma_f32_16x16x32_bf16 v[116:119], v[162:165], v[190:193], v[116:119]
	v_mfma_f32_16x16x32_bf16 v[112:115], v[180:183], v[190:193], v[112:115]
	v_mfma_f32_16x16x32_bf16 v[100:103], v[162:165], v[198:201], v[100:103]
	v_mfma_f32_16x16x32_bf16 v[96:99], v[180:183], v[198:201], v[96:99]
	v_mfma_f32_16x16x32_bf16 v[84:87], v[162:165], v[206:209], v[84:87]
	v_mfma_f32_16x16x32_bf16 v[80:83], v[180:183], v[206:209], v[80:83]
	v_mfma_f32_16x16x32_bf16 v[68:71], v[162:165], v[214:217], v[68:71]
	v_mfma_f32_16x16x32_bf16 v[64:67], v[180:183], v[214:217], v[64:67]
	v_mfma_f32_16x16x32_bf16 v[116:119], v[166:169], v[194:197], v[116:119]
	v_mfma_f32_16x16x32_bf16 v[112:115], v[184:187], v[194:197], v[112:115]
	v_mfma_f32_16x16x32_bf16 v[100:103], v[166:169], v[202:205], v[100:103]
	v_mfma_f32_16x16x32_bf16 v[96:99], v[184:187], v[202:205], v[96:99]
	v_mfma_f32_16x16x32_bf16 v[84:87], v[166:169], v[210:213], v[84:87]
	v_mfma_f32_16x16x32_bf16 v[80:83], v[184:187], v[210:213], v[80:83]
	v_mfma_f32_16x16x32_bf16 v[68:71], v[166:169], v[218:221], v[68:71]
	v_mfma_f32_16x16x32_bf16 v[64:67], v[184:187], v[218:221], v[64:67]
	s_setprio 0
	s_barrier
	s_add_u32 s98, s40, s14
	s_addc_u32 s99, s41, s15
	s_add_u32 s100, s42, s14
	s_addc_u32 s101, s43, s15
	s_add_i32 s8, s76, s46
	s_mov_b32 m0, s8
	ds_read_b128 v[190:193], v176 offset:16384
	ds_read_b128 v[194:197], v176 offset:17408
	ds_read_b128 v[198:201], v176 offset:18432
	ds_read_b128 v[202:205], v176 offset:19456
	ds_read_b128 v[206:209], v176 offset:20480
	ds_read_b128 v[210:213], v176 offset:21504
	ds_read_b128 v[214:217], v176 offset:22528
	ds_read_b128 v[218:221], v176 offset:23552
	global_load_lds_dwordx4 v146, s[40:41]
	s_add_i32 m0, s8, 0x2000
	s_add_u32 s8, s40, 0x40000
	s_addc_u32 s9, s41, 0
	s_add_i32 s54, s77, s46
	global_load_lds_dwordx4 v150, s[40:41]
	s_mov_b32 m0, s54
	s_nop 0
	global_load_lds_dwordx4 v146, s[8:9]
	s_add_i32 m0, s54, 0x2000
	s_nop 0
	global_load_lds_dwordx4 v150, s[8:9]
	s_mov_b32 m0, s47
	s_nop 0
	global_load_lds_dwordx4 v144, s[42:43]
	s_mov_b32 m0, s48
	s_nop 0
	global_load_lds_dwordx4 v148, s[42:43]
	s_waitcnt vmcnt(8)
	s_waitcnt lgkmcnt(0)
	s_barrier
	s_setprio 1
	v_mfma_f32_16x16x32_bf16 v[60:63], v[128:131], v[190:193], v[60:63]
	v_mfma_f32_16x16x32_bf16 v[56:59], v[136:139], v[190:193], v[56:59]
	v_mfma_f32_16x16x32_bf16 v[44:47], v[128:131], v[198:201], v[44:47]
	v_mfma_f32_16x16x32_bf16 v[40:43], v[136:139], v[198:201], v[40:43]
	v_mfma_f32_16x16x32_bf16 v[28:31], v[128:131], v[206:209], v[28:31]
	v_mfma_f32_16x16x32_bf16 v[24:27], v[136:139], v[206:209], v[24:27]
	v_mfma_f32_16x16x32_bf16 v[12:15], v[128:131], v[214:217], v[12:15]
	v_mfma_f32_16x16x32_bf16 v[8:11], v[136:139], v[214:217], v[8:11]
	v_mfma_f32_16x16x32_bf16 v[60:63], v[132:135], v[194:197], v[60:63]
	v_mfma_f32_16x16x32_bf16 v[56:59], v[140:143], v[194:197], v[56:59]
	v_mfma_f32_16x16x32_bf16 v[44:47], v[132:135], v[202:205], v[44:47]
	v_mfma_f32_16x16x32_bf16 v[40:43], v[140:143], v[202:205], v[40:43]
	v_mfma_f32_16x16x32_bf16 v[28:31], v[132:135], v[210:213], v[28:31]
	v_mfma_f32_16x16x32_bf16 v[24:27], v[140:143], v[210:213], v[24:27]
	v_mfma_f32_16x16x32_bf16 v[12:15], v[132:135], v[218:221], v[12:15]
	v_mfma_f32_16x16x32_bf16 v[8:11], v[140:143], v[218:221], v[8:11]
	v_mfma_f32_16x16x32_bf16 v[52:55], v[162:165], v[190:193], v[52:55]
	v_mfma_f32_16x16x32_bf16 v[48:51], v[180:183], v[190:193], v[48:51]
	v_mfma_f32_16x16x32_bf16 v[36:39], v[162:165], v[198:201], v[36:39]
	v_mfma_f32_16x16x32_bf16 v[32:35], v[180:183], v[198:201], v[32:35]
	v_mfma_f32_16x16x32_bf16 v[20:23], v[162:165], v[206:209], v[20:23]
	v_mfma_f32_16x16x32_bf16 v[16:19], v[180:183], v[206:209], v[16:19]
	v_mfma_f32_16x16x32_bf16 v[4:7], v[162:165], v[214:217], v[4:7]
	v_mfma_f32_16x16x32_bf16 v[0:3], v[180:183], v[214:217], v[0:3]
	v_mfma_f32_16x16x32_bf16 v[52:55], v[166:169], v[194:197], v[52:55]
	v_mfma_f32_16x16x32_bf16 v[48:51], v[184:187], v[194:197], v[48:51]
	v_mfma_f32_16x16x32_bf16 v[36:39], v[166:169], v[202:205], v[36:39]
	v_mfma_f32_16x16x32_bf16 v[32:35], v[184:187], v[202:205], v[32:35]
	v_mfma_f32_16x16x32_bf16 v[20:23], v[166:169], v[210:213], v[20:23]
	v_mfma_f32_16x16x32_bf16 v[16:19], v[184:187], v[210:213], v[16:19]
	v_mfma_f32_16x16x32_bf16 v[4:7], v[166:169], v[218:221], v[4:7]
	v_mfma_f32_16x16x32_bf16 v[0:3], v[184:187], v[218:221], v[0:3]
	s_setprio 0
	s_barrier
; #define PG8_STAGE(bufoff, gbase, voff) do { _Pragma("unroll") for (int _i = 0; _i < 2; ++_i) \
;         __builtin_amdgcn_global_load_lds((const unsigned*)((const char*)(gbase) + (voff)[_i]), (PG8_LAS unsigned*)(lds + (bufoff) + ldsw + _i * 8192), 16, 0, 0); } while (0)
; #define PG8_LDA(dst, b, h) do { _Pragma("unroll") for (int m = 0; m < 4; ++m) _Pragma("unroll") for (int k = 0; k < 2; ++k) dst[m][k] = *(const PG8_LAS bf16x8*)(lds + PG8_SA(b, h) + aoff + m * 2048 + k * 1024); } while (0)
; #define PG8_LDB(dst, b, h) do { _Pragma("unroll") for (int n = 0; n < 2; ++n) _Pragma("unroll") for (int k = 0; k < 2; ++k) dst[n][k] = *(const PG8_LAS bf16x8*)(lds + PG8_SB(b, h) + boff + n * 2048 + k * 1024); } while (0)
; #define PG8_MMA(ai, bj, At, Bt) do { __builtin_amdgcn_s_setprio(1); _Pragma("unroll") for (int m = 0; m < 4; ++m) _Pragma("unroll") for (int n = 0; n < 2; ++n) _Pragma("unroll") for (int k = 0; k < 2; ++k) \
;         acc[ai][bj][m][n] = __builtin_amdgcn_mfma_f32_16x16x32_bf16(Bt[n][k], At[m][k], acc[ai][bj][m][n], 0, 0, 0); __builtin_amdgcn_s_setprio(0); } while (0)
; #define PG8_WAIT_V(n) asm volatile("s_waitcnt vmcnt(" #n ")" ::: "memory")
; #define PG8_WAIT_L(n) asm volatile("s_waitcnt lgkmcnt(" #n ")" ::: "memory")
; #define PG8_BAR __builtin_amdgcn_s_barrier()
; #define PG8_SCHED __builtin_amdgcn_sched_barrier(0)
; template <class Epi, class Sched, bool ALIGN_EPI = false, bool SP2 = false>
; __device__ __forceinline__ void gemm_phase(PG8_LAS unsigned char* lds, const Gemm g, const Sched& S, const Epi& E) {
;     ...
;         for (int t = 0; t < nt; t += 2) {
;             const bool last = (t == nt - 2);
;             const char* a1 = cA + (size_t)(t + 1) * kstep;
;             const char* a2 = last ? nA : cA + (size_t)(t + 2) * kstep; const char* b2 = last ? nB : cB + (size_t)(t + 2) * kstep;
;     ...
;             PG8_LDB(B0, 1, 0); PG8_LDB(B1, 1, 1); PG8_SCHED; PG8_LDA(At, 1, 0); PG8_STAGE(PG8_SA(0, 1), a2 + hstep, voffA);
;             PG8_WAIT_V(8); PG8_WAIT_L(0); PG8_BAR; PG8_MMA(0, 0, At, B0); PG8_MMA(0, 1, At, B1); PG8_BAR; PG8_SCHED;
;             PG8_LDA(At, 1, 1); PG8_STAGE(PG8_SB(1, 0), b3, voffB); PG8_STAGE(PG8_SB(1, 1), b3 + hstep, voffB); PG8_STAGE(PG8_SA(1, 0), a3, voffA);
;             PG8_WAIT_V(8); PG8_WAIT_L(0); PG8_BAR; PG8_MMA(1, 0, At, B0); PG8_MMA(1, 1, At, B1); PG8_BAR; PG8_SCHED;
.Lmy_peel_684_mid:
	s_add_i32 s54, 0, 0x18000
	s_add_i32 s55, 0, 0x1c000
	v_add_u32_e32 v140, s54, v172
	v_add_u32_e32 v152, s55, v172
	ds_read_b128 v[128:131], v140
	ds_read_b128 v[132:135], v140 offset:1024
	ds_read_b128 v[136:139], v140 offset:2048
	ds_read_b128 v[140:143], v140 offset:3072
	ds_read_b128 v[162:165], v152
	ds_read_b128 v[166:169], v152 offset:1024
	ds_read_b128 v[180:183], v152 offset:2048
	ds_read_b128 v[184:187], v152 offset:3072
	s_add_u32 s8, s42, 0x40000
	s_addc_u32 s9, s43, 0
	s_mov_b32 m0, s49
	ds_read_b128 v[190:193], v176 offset:32768
	ds_read_b128 v[194:197], v176 offset:33792
	ds_read_b128 v[198:201], v176 offset:34816
	ds_read_b128 v[202:205], v176 offset:35840
	ds_read_b128 v[206:209], v176 offset:36864
	ds_read_b128 v[210:213], v176 offset:37888
	ds_read_b128 v[214:217], v176 offset:38912
	ds_read_b128 v[218:221], v176 offset:39936
	global_load_lds_dwordx4 v144, s[8:9]
	s_mov_b32 m0, s51
	s_nop 0
	global_load_lds_dwordx4 v148, s[8:9]
	s_waitcnt vmcnt(8)
	s_waitcnt lgkmcnt(0)
	s_barrier
	s_setprio 1
	v_mfma_f32_16x16x32_bf16 v[124:127], v[128:131], v[190:193], v[124:127]
	v_mfma_f32_16x16x32_bf16 v[120:123], v[136:139], v[190:193], v[120:123]
	v_mfma_f32_16x16x32_bf16 v[108:111], v[128:131], v[198:201], v[108:111]
	v_mfma_f32_16x16x32_bf16 v[104:107], v[136:139], v[198:201], v[104:107]
	v_mfma_f32_16x16x32_bf16 v[92:95], v[128:131], v[206:209], v[92:95]
	v_mfma_f32_16x16x32_bf16 v[88:91], v[136:139], v[206:209], v[88:91]
	v_mfma_f32_16x16x32_bf16 v[76:79], v[128:131], v[214:217], v[76:79]
	v_mfma_f32_16x16x32_bf16 v[72:75], v[136:139], v[214:217], v[72:75]
	v_mfma_f32_16x16x32_bf16 v[124:127], v[132:135], v[194:197], v[124:127]
	v_mfma_f32_16x16x32_bf16 v[120:123], v[140:143], v[194:197], v[120:123]
	v_mfma_f32_16x16x32_bf16 v[108:111], v[132:135], v[202:205], v[108:111]
	v_mfma_f32_16x16x32_bf16 v[104:107], v[140:143], v[202:205], v[104:107]
	v_mfma_f32_16x16x32_bf16 v[92:95], v[132:135], v[210:213], v[92:95]
	v_mfma_f32_16x16x32_bf16 v[88:91], v[140:143], v[210:213], v[88:91]
	v_mfma_f32_16x16x32_bf16 v[76:79], v[132:135], v[218:221], v[76:79]
	v_mfma_f32_16x16x32_bf16 v[72:75], v[140:143], v[218:221], v[72:75]
	v_mfma_f32_16x16x32_bf16 v[116:119], v[162:165], v[190:193], v[116:119]
	v_mfma_f32_16x16x32_bf16 v[112:115], v[180:183], v[190:193], v[112:115]
	v_mfma_f32_16x16x32_bf16 v[100:103], v[162:165], v[198:201], v[100:103]
	v_mfma_f32_16x16x32_bf16 v[96:99], v[180:183], v[198:201], v[96:99]
	v_mfma_f32_16x16x32_bf16 v[84:87], v[162:165], v[206:209], v[84:87]
	v_mfma_f32_16x16x32_bf16 v[80:83], v[180:183], v[206:209], v[80:83]
	v_mfma_f32_16x16x32_bf16 v[68:71], v[162:165], v[214:217], v[68:71]
	v_mfma_f32_16x16x32_bf16 v[64:67], v[180:183], v[214:217], v[64:67]
	v_mfma_f32_16x16x32_bf16 v[116:119], v[166:169], v[194:197], v[116:119]
	v_mfma_f32_16x16x32_bf16 v[112:115], v[184:187], v[194:197], v[112:115]
	v_mfma_f32_16x16x32_bf16 v[100:103], v[166:169], v[202:205], v[100:103]
	v_mfma_f32_16x16x32_bf16 v[96:99], v[184:187], v[202:205], v[96:99]
	v_mfma_f32_16x16x32_bf16 v[84:87], v[166:169], v[210:213], v[84:87]
	v_mfma_f32_16x16x32_bf16 v[80:83], v[184:187], v[210:213], v[80:83]
	v_mfma_f32_16x16x32_bf16 v[68:71], v[166:169], v[218:221], v[68:71]
	v_mfma_f32_16x16x32_bf16 v[64:67], v[184:187], v[218:221], v[64:67]
	s_setprio 0
	s_barrier
	s_add_i32 s8, s54, s46
	s_mov_b32 m0, s8
	ds_read_b128 v[190:193], v176 offset:49152
	ds_read_b128 v[194:197], v176 offset:50176
	ds_read_b128 v[198:201], v176 offset:51200
	ds_read_b128 v[202:205], v176 offset:52224
	ds_read_b128 v[206:209], v176 offset:53248
	ds_read_b128 v[210:213], v176 offset:54272
	ds_read_b128 v[214:217], v176 offset:55296
	ds_read_b128 v[218:221], v176 offset:56320
	global_load_lds_dwordx4 v146, s[98:99]
	s_add_i32 m0, s8, 0x2000
	s_add_u32 s8, s40, 0x40080
	s_addc_u32 s9, s41, 0
	s_add_i32 s40, s55, s46
	global_load_lds_dwordx4 v150, s[98:99]
	s_mov_b32 m0, s40
	s_nop 0
	global_load_lds_dwordx4 v146, s[8:9]
	s_add_i32 m0, s40, 0x2000
	s_nop 0
	global_load_lds_dwordx4 v150, s[8:9]
	s_mov_b32 m0, s66
	s_nop 0
	global_load_lds_dwordx4 v144, s[100:101]
	s_mov_b32 m0, s67
	s_nop 0
	global_load_lds_dwordx4 v148, s[100:101]
	s_waitcnt vmcnt(8)
	s_waitcnt lgkmcnt(0)
	s_barrier
	s_setprio 1
	v_mfma_f32_16x16x32_bf16 v[60:63], v[128:131], v[190:193], v[60:63]
	v_mfma_f32_16x16x32_bf16 v[56:59], v[136:139], v[190:193], v[56:59]
	v_mfma_f32_16x16x32_bf16 v[44:47], v[128:131], v[198:201], v[44:47]
	v_mfma_f32_16x16x32_bf16 v[40:43], v[136:139], v[198:201], v[40:43]
	v_mfma_f32_16x16x32_bf16 v[28:31], v[128:131], v[206:209], v[28:31]
	v_mfma_f32_16x16x32_bf16 v[24:27], v[136:139], v[206:209], v[24:27]
	v_mfma_f32_16x16x32_bf16 v[12:15], v[128:131], v[214:217], v[12:15]
	v_mfma_f32_16x16x32_bf16 v[8:11], v[136:139], v[214:217], v[8:11]
	v_mfma_f32_16x16x32_bf16 v[60:63], v[132:135], v[194:197], v[60:63]
	v_mfma_f32_16x16x32_bf16 v[56:59], v[140:143], v[194:197], v[56:59]
	v_mfma_f32_16x16x32_bf16 v[44:47], v[132:135], v[202:205], v[44:47]
	v_mfma_f32_16x16x32_bf16 v[40:43], v[140:143], v[202:205], v[40:43]
	v_mfma_f32_16x16x32_bf16 v[28:31], v[132:135], v[210:213], v[28:31]
	v_mfma_f32_16x16x32_bf16 v[24:27], v[140:143], v[210:213], v[24:27]
	v_mfma_f32_16x16x32_bf16 v[12:15], v[132:135], v[218:221], v[12:15]
	v_mfma_f32_16x16x32_bf16 v[8:11], v[140:143], v[218:221], v[8:11]
	v_mfma_f32_16x16x32_bf16 v[52:55], v[162:165], v[190:193], v[52:55]
	v_mfma_f32_16x16x32_bf16 v[48:51], v[180:183], v[190:193], v[48:51]
	v_mfma_f32_16x16x32_bf16 v[36:39], v[162:165], v[198:201], v[36:39]
	v_mfma_f32_16x16x32_bf16 v[32:35], v[180:183], v[198:201], v[32:35]
	v_mfma_f32_16x16x32_bf16 v[20:23], v[162:165], v[206:209], v[20:23]
	v_mfma_f32_16x16x32_bf16 v[16:19], v[180:183], v[206:209], v[16:19]
	v_mfma_f32_16x16x32_bf16 v[4:7], v[162:165], v[214:217], v[4:7]
	v_mfma_f32_16x16x32_bf16 v[0:3], v[180:183], v[214:217], v[0:3]
	v_mfma_f32_16x16x32_bf16 v[52:55], v[166:169], v[194:197], v[52:55]
	v_mfma_f32_16x16x32_bf16 v[48:51], v[184:187], v[194:197], v[48:51]
	v_mfma_f32_16x16x32_bf16 v[36:39], v[166:169], v[202:205], v[36:39]
	v_mfma_f32_16x16x32_bf16 v[32:35], v[184:187], v[202:205], v[32:35]
	v_mfma_f32_16x16x32_bf16 v[20:23], v[166:169], v[210:213], v[20:23]
	v_mfma_f32_16x16x32_bf16 v[16:19], v[184:187], v[210:213], v[16:19]
	v_mfma_f32_16x16x32_bf16 v[4:7], v[166:169], v[218:221], v[4:7]
	v_mfma_f32_16x16x32_bf16 v[0:3], v[184:187], v[218:221], v[0:3]
	s_setprio 0
	s_barrier
	s_add_i32 vcc_lo, vcc_lo, 2
	s_add_u32 s0, s0, 0x100
	s_addc_u32 s1, s1, 0
	s_add_u32 s96, s96, 0x100
	s_addc_u32 s97, s97, 0
	s_cmp_gt_u32 vcc_lo, 13
	s_cbranch_scc0 .LBB0_684
	s_and_b64 vcc, exec, s[18:19]
	s_cbranch_vccz .LBB0_687
	s_barrier
